# FFN1 epilogue conv parameters: one distributed load by the wr=0 waves, staged in the unused 4 KB behind the halo exchange area, LDS broadcast reads by all waves (was 16 row-broadcast global loads per
# baseline (speedup 1.0000x reference)
; #define PG8_STAGE(bufoff, gbase, voff) do { _Pragma("unroll") for (int _i = 0; _i < 2; ++_i) \
;         __builtin_amdgcn_global_load_lds((const unsigned*)((const char*)(gbase) + (voff)[_i]), (LAS unsigned*)(lds + (bufoff) + ldsw + _i * 8192), 16, 0, 0); } while (0)
; #define PG8_LDA(dst, b, h) do { _Pragma("unroll") for (int m = 0; m < 4; ++m) _Pragma("unroll") for (int k = 0; k < 2; ++k) dst[m][k] = *(const LAS bf16x8*)(lds + PG8_SA(b, h) + aoff + m * 2048 + k * 1024); } while (0)
; #define PG8_LDB(dst, b, h) do { _Pragma("unroll") for (int n = 0; n < 2; ++n) _Pragma("unroll") for (int k = 0; k < 2; ++k) dst[n][k] = *(const LAS bf16x8*)(lds + PG8_SB(b, h) + boff + n * 2048 + k * 1024); } while (0)
; #define PG8_MMA(ai, bj, At, Bt) do { __builtin_amdgcn_s_setprio(1); _Pragma("unroll") for (int m = 0; m < 4; ++m) _Pragma("unroll") for (int n = 0; n < 2; ++n) _Pragma("unroll") for (int k = 0; k < 2; ++k) \
;         acc[ai][bj][m][n] = __builtin_amdgcn_mfma_f32_16x16x32_bf16(Bt[n][k], At[m][k], acc[ai][bj][m][n], 0, 0, 0); __builtin_amdgcn_s_setprio(0); } while (0)
; #define PG8_WAIT_V(n) asm volatile("s_waitcnt vmcnt(" #n ")" ::: "memory")
; #define PG8_WAIT_L(n) asm volatile("s_waitcnt lgkmcnt(" #n ")" ::: "memory")
; #define PG8_BAR __builtin_amdgcn_s_barrier()
; #define PG8_SCHED __builtin_amdgcn_sched_barrier(0)
; template <class Epi>
; __device__ __forceinline__ void gemm_phase(LAS unsigned char* lds, const Gemm g, const StaticOrder& S, const Epi& E) {
;     ...
;             PG8_LDB(B0, 0, 0); PG8_SCHED; PG8_LDA(At, 0, 0); PG8_STAGE(PG8_SA(1, 1), a1 + hstepA, voffA);
;             PG8_WAIT_L(8); PG8_BAR; PG8_WAIT_L(0); PG8_MMA(0, 0, At, B0); PG8_BAR; PG8_SCHED;
;             PG8_LDB(B1, 0, 1); PG8_STAGE(PG8_SB(0, 0), b2, voffB);
;             PG8_BAR; PG8_WAIT_L(0); PG8_MMA(0, 1, At, B1); PG8_BAR;
;             PG8_LDA(At, 0, 1); PG8_STAGE(PG8_SA(0, 0), a2, voffA);
;             PG8_BAR; PG8_WAIT_L(0); PG8_MMA(1, 0, At, B0); PG8_BAR; PG8_SCHED;
;             PG8_STAGE(PG8_SB(0, 1), b2 + hstepB, voffB);
;             PG8_WAIT_V(6); PG8_BAR; PG8_MMA(1, 1, At, B1); PG8_BAR;
.LBB0_309:
	ds_read_b128 v[96:99], v243
	ds_read_b128 v[100:103], v243 offset:1024
	ds_read_b128 v[104:107], v243 offset:2048
	ds_read_b128 v[108:111], v243 offset:3072
	s_add_u32 s38, s36, 0x100
	s_addc_u32 s39, s37, 0
	s_cmp_eq_u32 s79, 12
	s_cselect_b32 s43, s27, s39
	s_cselect_b32 s42, s75, s38
	s_cselect_b32 s41, s25, s78
	s_cselect_b32 s40, s76, s77
	v_lshl_add_u64 v[176:177], s[36:37], 0, v[224:225]
	s_add_i32 m0, s45, 0xc000
	ds_read_b128 v[112:115], v244
	ds_read_b128 v[116:119], v244 offset:1024
	ds_read_b128 v[120:123], v244 offset:2048
	ds_read_b128 v[124:127], v244 offset:3072
	ds_read_b128 v[160:163], v244 offset:4096
	ds_read_b128 v[164:167], v244 offset:5120
	ds_read_b128 v[168:171], v244 offset:6144
	ds_read_b128 v[172:175], v244 offset:7168
	global_load_lds_dwordx4 v[176:177], off
	v_lshl_add_u64 v[176:177], s[36:37], 0, v[226:227]
	s_add_i32 m0, s45, 0xe000
	s_nop 0
	global_load_lds_dwordx4 v[176:177], off
	ds_read_b128 v[176:179], v245
	ds_read_b128 v[180:183], v245 offset:1024
	ds_read_b128 v[184:187], v245 offset:2048
	ds_read_b128 v[188:191], v245 offset:3072
	s_waitcnt lgkmcnt(0)
	s_barrier
	s_setprio 1
	v_mfma_f32_16x16x32_bf16 v[156:159], v[96:99], v[112:115], v[156:159]
	v_mfma_f32_16x16x32_bf16 v[60:63], v[104:107], v[112:115], v[60:63]
	v_mfma_f32_16x16x32_bf16 v[144:147], v[96:99], v[120:123], v[144:147]
	v_mfma_f32_16x16x32_bf16 v[48:51], v[104:107], v[120:123], v[48:51]
	v_mfma_f32_16x16x32_bf16 v[136:139], v[96:99], v[160:163], v[136:139]
	v_mfma_f32_16x16x32_bf16 v[40:43], v[104:107], v[160:163], v[40:43]
	v_mfma_f32_16x16x32_bf16 v[148:151], v[96:99], v[168:171], v[148:151]
	v_mfma_f32_16x16x32_bf16 v[52:55], v[104:107], v[168:171], v[52:55]
	v_mfma_f32_16x16x32_bf16 v[156:159], v[100:103], v[116:119], v[156:159]
	v_mfma_f32_16x16x32_bf16 v[60:63], v[108:111], v[116:119], v[60:63]
	v_mfma_f32_16x16x32_bf16 v[144:147], v[100:103], v[124:127], v[144:147]
	v_mfma_f32_16x16x32_bf16 v[48:51], v[108:111], v[124:127], v[48:51]
	v_mfma_f32_16x16x32_bf16 v[136:139], v[100:103], v[164:167], v[136:139]
	v_mfma_f32_16x16x32_bf16 v[40:43], v[108:111], v[164:167], v[40:43]
	v_mfma_f32_16x16x32_bf16 v[148:151], v[100:103], v[172:175], v[148:151]
	v_mfma_f32_16x16x32_bf16 v[52:55], v[108:111], v[172:175], v[52:55]
	v_mfma_f32_16x16x32_bf16 v[152:155], v[176:179], v[112:115], v[152:155]
	v_mfma_f32_16x16x32_bf16 v[56:59], v[184:187], v[112:115], v[56:59]
	v_mfma_f32_16x16x32_bf16 v[36:39], v[184:187], v[120:123], v[36:39]
	v_mfma_f32_16x16x32_bf16 v[32:35], v[184:187], v[160:163], v[32:35]
	v_mfma_f32_16x16x32_bf16 v[44:47], v[184:187], v[168:171], v[44:47]
	v_mfma_f32_16x16x32_bf16 v[152:155], v[180:183], v[116:119], v[152:155]
	v_mfma_f32_16x16x32_bf16 v[56:59], v[188:191], v[116:119], v[56:59]
	v_mfma_f32_16x16x32_bf16 v[112:115], v[176:179], v[120:123], v[132:135]
	v_mfma_f32_16x16x32_bf16 v[36:39], v[188:191], v[124:127], v[36:39]
	v_mfma_f32_16x16x32_bf16 v[116:119], v[176:179], v[160:163], v[128:131]
	v_mfma_f32_16x16x32_bf16 v[32:35], v[188:191], v[164:167], v[32:35]
	v_mfma_f32_16x16x32_bf16 v[120:123], v[176:179], v[168:171], v[140:143]
	v_mfma_f32_16x16x32_bf16 v[44:47], v[188:191], v[172:175], v[44:47]
	v_mfma_f32_16x16x32_bf16 v[112:115], v[180:183], v[124:127], v[112:115]
	v_mfma_f32_16x16x32_bf16 v[116:119], v[180:183], v[164:167], v[116:119]
	v_mfma_f32_16x16x32_bf16 v[120:123], v[180:183], v[172:175], v[120:123]
	s_setprio 0
	s_barrier
	s_nop 1
	ds_read_b128 v[124:127], v244 offset:16384
	ds_read_b128 v[128:131], v244 offset:17408
	ds_read_b128 v[132:135], v244 offset:18432
	ds_read_b128 v[140:143], v244 offset:19456
	ds_read_b128 v[160:163], v244 offset:20480
	ds_read_b128 v[164:167], v244 offset:21504
	ds_read_b128 v[168:171], v244 offset:22528
	ds_read_b128 v[172:175], v244 offset:23552
	s_add_i32 s36, s72, s6
	v_lshl_add_u64 v[196:197], s[40:41], 0, v[214:215]
	s_mov_b32 m0, s36
	s_nop 0
	global_load_lds_dwordx4 v[196:197], off
	v_lshl_add_u64 v[198:199], s[40:41], 0, v[210:211]
	s_add_i32 m0, s36, 0x2000
	s_nop 0
	global_load_lds_dwordx4 v[198:199], off
	s_mov_b32 m0, s45
	v_lshl_add_u64 v[200:201], s[42:43], 0, v[216:217]
	global_load_lds_dwordx4 v[200:201], off
	v_lshl_add_u64 v[202:203], s[42:43], 0, v[212:213]
	s_mov_b32 m0, s46
	s_nop 0
	global_load_lds_dwordx4 v[202:203], off
	s_add_u32 s36, s40, 0x40000
	s_addc_u32 s37, s41, 0
	s_add_i32 s80, s73, s6
	v_lshl_add_u64 v[254:255], s[36:37], 0, v[214:215]
	s_mov_b32 m0, s80
	s_nop 0
	global_load_lds_dwordx4 v[254:255], off
	v_lshl_add_u64 v[254:255], s[36:37], 0, v[210:211]
	s_add_i32 m0, s80, 0x2000
	s_nop 0
	global_load_lds_dwordx4 v[254:255], off
	s_waitcnt vmcnt(6)
	s_waitcnt lgkmcnt(0)
	s_barrier
; #define PG8_STAGE(bufoff, gbase, voff) do { _Pragma("unroll") for (int _i = 0; _i < 2; ++_i) \
;         __builtin_amdgcn_global_load_lds((const unsigned*)((const char*)(gbase) + (voff)[_i]), (LAS unsigned*)(lds + (bufoff) + ldsw + _i * 8192), 16, 0, 0); } while (0)
; #define PG8_LDA(dst, b, h) do { _Pragma("unroll") for (int m = 0; m < 4; ++m) _Pragma("unroll") for (int k = 0; k < 2; ++k) dst[m][k] = *(const LAS bf16x8*)(lds + PG8_SA(b, h) + aoff + m * 2048 + k * 1024); } while (0)
; #define PG8_LDB(dst, b, h) do { _Pragma("unroll") for (int n = 0; n < 2; ++n) _Pragma("unroll") for (int k = 0; k < 2; ++k) dst[n][k] = *(const LAS bf16x8*)(lds + PG8_SB(b, h) + boff + n * 2048 + k * 1024); } while (0)
; #define PG8_MMA(ai, bj, At, Bt) do { __builtin_amdgcn_s_setprio(1); _Pragma("unroll") for (int m = 0; m < 4; ++m) _Pragma("unroll") for (int n = 0; n < 2; ++n) _Pragma("unroll") for (int k = 0; k < 2; ++k) \
;         acc[ai][bj][m][n] = __builtin_amdgcn_mfma_f32_16x16x32_bf16(Bt[n][k], At[m][k], acc[ai][bj][m][n], 0, 0, 0); __builtin_amdgcn_s_setprio(0); } while (0)
; #define PG8_WAIT_V(n) asm volatile("s_waitcnt vmcnt(" #n ")" ::: "memory")
; #define PG8_WAIT_L(n) asm volatile("s_waitcnt lgkmcnt(" #n ")" ::: "memory")
; #define PG8_BAR __builtin_amdgcn_s_barrier()
; #define PG8_SCHED __builtin_amdgcn_sched_barrier(0)
; template <class Epi>
; __device__ __forceinline__ void gemm_phase(LAS unsigned char* lds, const Gemm g, const StaticOrder& S, const Epi& E) {
;     ...
;             PG8_LDB(B1, 0, 1); PG8_STAGE(PG8_SB(0, 0), b2, voffB);
;             PG8_BAR; PG8_WAIT_L(0); PG8_MMA(0, 1, At, B1); PG8_BAR;
;             PG8_LDA(At, 0, 1); PG8_STAGE(PG8_SA(0, 0), a2, voffA);
;             PG8_BAR; PG8_WAIT_L(0); PG8_MMA(1, 0, At, B0); PG8_BAR; PG8_SCHED;
;             PG8_STAGE(PG8_SB(0, 1), b2 + hstepB, voffB);
;             PG8_WAIT_V(6); PG8_BAR; PG8_MMA(1, 1, At, B1); PG8_BAR;
;             PG8_LDB(B0, 1, 0); PG8_SCHED; PG8_LDA(At, 1, 0); PG8_STAGE(PG8_SA(0, 1), a2 + hstepA, voffA);
;             PG8_WAIT_L(8); PG8_BAR; PG8_WAIT_L(0); PG8_MMA(0, 0, At, B0); PG8_BAR; PG8_SCHED;
;             PG8_LDB(B1, 1, 1); PG8_STAGE(PG8_SB(1, 0), b3, voffB);
;             PG8_BAR; PG8_WAIT_L(0); PG8_MMA(0, 1, At, B1); PG8_BAR;
;             PG8_LDA(At, 1, 1); PG8_STAGE(PG8_SA(1, 0), a3, voffA);
;             PG8_BAR; PG8_WAIT_L(0); PG8_MMA(1, 0, At, B0); PG8_BAR; PG8_SCHED;
	s_setprio 1
	v_mfma_f32_16x16x32_bf16 v[92:95], v[96:99], v[124:127], v[92:95]
	v_mfma_f32_16x16x32_bf16 v[28:31], v[104:107], v[124:127], v[28:31]
	v_mfma_f32_16x16x32_bf16 v[80:83], v[96:99], v[132:135], v[80:83]
	v_mfma_f32_16x16x32_bf16 v[16:19], v[104:107], v[132:135], v[16:19]
	v_mfma_f32_16x16x32_bf16 v[76:79], v[96:99], v[160:163], v[76:79]
	v_mfma_f32_16x16x32_bf16 v[12:15], v[104:107], v[160:163], v[12:15]
	v_mfma_f32_16x16x32_bf16 v[84:87], v[96:99], v[168:171], v[84:87]
	v_mfma_f32_16x16x32_bf16 v[20:23], v[104:107], v[168:171], v[20:23]
	v_mfma_f32_16x16x32_bf16 v[92:95], v[100:103], v[128:131], v[92:95]
	v_mfma_f32_16x16x32_bf16 v[28:31], v[108:111], v[128:131], v[28:31]
	v_mfma_f32_16x16x32_bf16 v[80:83], v[100:103], v[140:143], v[80:83]
	v_mfma_f32_16x16x32_bf16 v[16:19], v[108:111], v[140:143], v[16:19]
	v_mfma_f32_16x16x32_bf16 v[76:79], v[100:103], v[164:167], v[76:79]
	v_mfma_f32_16x16x32_bf16 v[12:15], v[108:111], v[164:167], v[12:15]
	v_mfma_f32_16x16x32_bf16 v[84:87], v[100:103], v[172:175], v[84:87]
	v_mfma_f32_16x16x32_bf16 v[20:23], v[108:111], v[172:175], v[20:23]
	v_mfma_f32_16x16x32_bf16 v[88:91], v[176:179], v[124:127], v[88:91]
	v_mfma_f32_16x16x32_bf16 v[24:27], v[184:187], v[124:127], v[24:27]
	v_mfma_f32_16x16x32_bf16 v[68:71], v[176:179], v[132:135], v[68:71]
	v_mfma_f32_16x16x32_bf16 v[4:7], v[184:187], v[132:135], v[4:7]
	v_mfma_f32_16x16x32_bf16 v[64:67], v[176:179], v[160:163], v[64:67]
	v_mfma_f32_16x16x32_bf16 v[0:3], v[184:187], v[160:163], v[0:3]
	v_mfma_f32_16x16x32_bf16 v[72:75], v[176:179], v[168:171], v[72:75]
	v_mfma_f32_16x16x32_bf16 v[8:11], v[184:187], v[168:171], v[8:11]
	v_mfma_f32_16x16x32_bf16 v[88:91], v[180:183], v[128:131], v[88:91]
	v_mfma_f32_16x16x32_bf16 v[24:27], v[188:191], v[128:131], v[24:27]
	v_mfma_f32_16x16x32_bf16 v[68:71], v[180:183], v[140:143], v[68:71]
	v_mfma_f32_16x16x32_bf16 v[4:7], v[188:191], v[140:143], v[4:7]
	v_mfma_f32_16x16x32_bf16 v[64:67], v[180:183], v[164:167], v[64:67]
	v_mfma_f32_16x16x32_bf16 v[0:3], v[188:191], v[164:167], v[0:3]
	v_mfma_f32_16x16x32_bf16 v[72:75], v[180:183], v[172:175], v[72:75]
	v_mfma_f32_16x16x32_bf16 v[8:11], v[188:191], v[172:175], v[8:11]
	s_setprio 0
	s_add_i32 s80, 0, 0x18000
	v_add_u32_e32 v108, s80, v235
	s_barrier
	ds_read_b128 v[96:99], v108
	ds_read_b128 v[100:103], v108 offset:1024
	ds_read_b128 v[104:107], v108 offset:2048
	ds_read_b128 v[108:111], v108 offset:3072
	s_add_u32 s36, s42, 0x40000
	s_addc_u32 s37, s43, 0
	s_mov_b32 m0, s47
	v_lshl_add_u64 v[132:133], s[36:37], 0, v[216:217]
	ds_read_b128 v[124:127], v244 offset:32768
	ds_read_b128 v[128:131], v244 offset:33792
	ds_read_b128 v[140:143], v244 offset:34816
	ds_read_b128 v[160:163], v244 offset:35840
	ds_read_b128 v[164:167], v244 offset:36864
	ds_read_b128 v[168:171], v244 offset:37888
	ds_read_b128 v[172:175], v244 offset:38912
	ds_read_b128 v[176:179], v244 offset:39936
	global_load_lds_dwordx4 v[132:133], off
	v_lshl_add_u64 v[132:133], s[36:37], 0, v[212:213]
	s_mov_b32 m0, s48
	s_nop 0
	global_load_lds_dwordx4 v[132:133], off
	s_add_i32 s42, 0, 0x1c000
	v_add_u32_e32 v132, s42, v235
	ds_read_b128 v[180:183], v132
	ds_read_b128 v[184:187], v132 offset:1024
	ds_read_b128 v[188:191], v132 offset:2048
	ds_read_b128 v[192:195], v132 offset:3072
	s_waitcnt lgkmcnt(0)
	s_barrier
	s_setprio 1
	v_mfma_f32_16x16x32_bf16 v[132:135], v[96:99], v[124:127], v[156:159]
	v_mfma_f32_16x16x32_bf16 v[156:159], v[100:103], v[128:131], v[132:135]
	v_mfma_f32_16x16x32_bf16 v[132:135], v[96:99], v[140:143], v[144:147]
	v_mfma_f32_16x16x32_bf16 v[144:147], v[100:103], v[160:163], v[132:135]
	v_mfma_f32_16x16x32_bf16 v[132:135], v[96:99], v[164:167], v[136:139]
	v_mfma_f32_16x16x32_bf16 v[60:63], v[104:107], v[124:127], v[60:63]
	v_mfma_f32_16x16x32_bf16 v[48:51], v[104:107], v[140:143], v[48:51]
	v_mfma_f32_16x16x32_bf16 v[136:139], v[100:103], v[168:171], v[132:135]
	v_mfma_f32_16x16x32_bf16 v[40:43], v[104:107], v[164:167], v[40:43]
	v_mfma_f32_16x16x32_bf16 v[132:135], v[96:99], v[172:175], v[148:151]
	v_mfma_f32_16x16x32_bf16 v[52:55], v[104:107], v[172:175], v[52:55]
	v_mfma_f32_16x16x32_bf16 v[60:63], v[108:111], v[128:131], v[60:63]
	v_mfma_f32_16x16x32_bf16 v[48:51], v[108:111], v[160:163], v[48:51]
	v_mfma_f32_16x16x32_bf16 v[40:43], v[108:111], v[168:171], v[40:43]
	v_mfma_f32_16x16x32_bf16 v[148:151], v[100:103], v[176:179], v[132:135]
	v_mfma_f32_16x16x32_bf16 v[52:55], v[108:111], v[176:179], v[52:55]
	v_mfma_f32_16x16x32_bf16 v[132:135], v[180:183], v[124:127], v[152:155]
	v_mfma_f32_16x16x32_bf16 v[112:115], v[180:183], v[140:143], v[112:115]
	v_mfma_f32_16x16x32_bf16 v[152:155], v[184:187], v[128:131], v[132:135]
	v_mfma_f32_16x16x32_bf16 v[56:59], v[188:191], v[124:127], v[56:59]
	v_mfma_f32_16x16x32_bf16 v[132:135], v[184:187], v[160:163], v[112:115]
	v_mfma_f32_16x16x32_bf16 v[112:115], v[180:183], v[164:167], v[116:119]
	v_mfma_f32_16x16x32_bf16 v[56:59], v[192:195], v[128:131], v[56:59]
	v_mfma_f32_16x16x32_bf16 v[36:39], v[188:191], v[140:143], v[36:39]
	v_mfma_f32_16x16x32_bf16 v[128:131], v[184:187], v[168:171], v[112:115]
	v_mfma_f32_16x16x32_bf16 v[32:35], v[188:191], v[164:167], v[32:35]
	v_mfma_f32_16x16x32_bf16 v[112:115], v[180:183], v[172:175], v[120:123]
	v_mfma_f32_16x16x32_bf16 v[44:47], v[188:191], v[172:175], v[44:47]
	v_mfma_f32_16x16x32_bf16 v[36:39], v[192:195], v[160:163], v[36:39]
	v_mfma_f32_16x16x32_bf16 v[32:35], v[192:195], v[168:171], v[32:35]
	v_mfma_f32_16x16x32_bf16 v[140:143], v[184:187], v[176:179], v[112:115]
	v_mfma_f32_16x16x32_bf16 v[44:47], v[192:195], v[176:179], v[44:47]
	s_setprio 0
	s_barrier
; #define PG8_STAGE(bufoff, gbase, voff) do { _Pragma("unroll") for (int _i = 0; _i < 2; ++_i) \
;         __builtin_amdgcn_global_load_lds((const unsigned*)((const char*)(gbase) + (voff)[_i]), (LAS unsigned*)(lds + (bufoff) + ldsw + _i * 8192), 16, 0, 0); } while (0)
; #define PG8_LDA(dst, b, h) do { _Pragma("unroll") for (int m = 0; m < 4; ++m) _Pragma("unroll") for (int k = 0; k < 2; ++k) dst[m][k] = *(const LAS bf16x8*)(lds + PG8_SA(b, h) + aoff + m * 2048 + k * 1024); } while (0)
; #define PG8_LDB(dst, b, h) do { _Pragma("unroll") for (int n = 0; n < 2; ++n) _Pragma("unroll") for (int k = 0; k < 2; ++k) dst[n][k] = *(const LAS bf16x8*)(lds + PG8_SB(b, h) + boff + n * 2048 + k * 1024); } while (0)
; #define PG8_MMA(ai, bj, At, Bt) do { __builtin_amdgcn_s_setprio(1); _Pragma("unroll") for (int m = 0; m < 4; ++m) _Pragma("unroll") for (int n = 0; n < 2; ++n) _Pragma("unroll") for (int k = 0; k < 2; ++k) \
;         acc[ai][bj][m][n] = __builtin_amdgcn_mfma_f32_16x16x32_bf16(Bt[n][k], At[m][k], acc[ai][bj][m][n], 0, 0, 0); __builtin_amdgcn_s_setprio(0); } while (0)
; #define PG8_WAIT_V(n) asm volatile("s_waitcnt vmcnt(" #n ")" ::: "memory")
; #define PG8_WAIT_L(n) asm volatile("s_waitcnt lgkmcnt(" #n ")" ::: "memory")
; template <class Epi>
; __device__ __forceinline__ void gemm_phase(LAS unsigned char* lds, const Gemm g, const StaticOrder& S, const Epi& E) {
;     ...
;             PG8_LDB(B1, 1, 1); PG8_STAGE(PG8_SB(1, 0), b3, voffB);
;             PG8_BAR; PG8_WAIT_L(0); PG8_MMA(0, 1, At, B1); PG8_BAR;
;             PG8_LDA(At, 1, 1); PG8_STAGE(PG8_SA(1, 0), a3, voffA);
;             PG8_BAR; PG8_WAIT_L(0); PG8_MMA(1, 0, At, B0); PG8_BAR; PG8_SCHED;
;             PG8_STAGE(PG8_SB(1, 1), b3 + hstepB, voffB);
;             PG8_WAIT_V(6); PG8_BAR; PG8_MMA(1, 1, At, B1); PG8_BAR;
;     __device__ __forceinline__ void operator()(AccRef acc, const Unit& u, int wr, int wc, int fr, int fq) const {
;     ...
;         f32x4 cwv[2][8];
;         { const float* cv = cw + 128 * u.pn + clb; const float* cg = cv + FH; const float* bp = cb + 128 * u.pn + clb;
;           cwv[0][0] = *(const f32x4*)(cv); cwv[0][1] = *(const f32x4*)(cv + F2); cwv[0][2] = *(const f32x4*)(cv + 2 * F2); cwv[0][3] = *(const f32x4*)(bp);
;           cwv[0][4] = *(const f32x4*)(cg); cwv[0][5] = *(const f32x4*)(cg + F2); cwv[0][6] = *(const f32x4*)(cg + 2 * F2); cwv[0][7] = *(const f32x4*)(bp + FH); }
	s_nop 1
	ds_read_b128 v[112:115], v244 offset:49152
	ds_read_b128 v[116:119], v244 offset:50176
	ds_read_b128 v[120:123], v244 offset:51200
	ds_read_b128 v[124:127], v244 offset:52224
	ds_read_b128 v[160:163], v244 offset:53248
	ds_read_b128 v[164:167], v244 offset:54272
	ds_read_b128 v[168:171], v244 offset:55296
	ds_read_b128 v[172:175], v244 offset:56320
	s_add_i32 s36, s80, s6
	v_lshl_add_u64 v[254:255], v[196:197], 0, s[14:15]
	s_mov_b32 m0, s36
	s_nop 0
	global_load_lds_dwordx4 v[254:255], off
	v_lshl_add_u64 v[254:255], v[198:199], 0, s[14:15]
	s_add_i32 m0, s36, 0x2000
	s_nop 0
	global_load_lds_dwordx4 v[254:255], off
	s_mov_b32 m0, s68
	v_lshl_add_u64 v[254:255], v[200:201], 0, s[14:15]
	global_load_lds_dwordx4 v[254:255], off
	v_lshl_add_u64 v[254:255], v[202:203], 0, s[14:15]
	s_mov_b32 m0, s69
	s_nop 0
	global_load_lds_dwordx4 v[254:255], off
	s_add_u32 s36, s40, 0x40080
	s_addc_u32 s37, s41, 0
	s_add_i32 s40, s42, s6
	v_lshl_add_u64 v[254:255], s[36:37], 0, v[214:215]
	s_mov_b32 m0, s40
	s_nop 0
	global_load_lds_dwordx4 v[254:255], off
	v_lshl_add_u64 v[254:255], s[36:37], 0, v[210:211]
	s_add_i32 m0, s40, 0x2000
	s_nop 0
	global_load_lds_dwordx4 v[254:255], off
	s_waitcnt vmcnt(6)
	s_waitcnt lgkmcnt(0)
	s_barrier
	s_setprio 1
	v_mfma_f32_16x16x32_bf16 v[92:95], v[96:99], v[112:115], v[92:95]
	v_mfma_f32_16x16x32_bf16 v[28:31], v[104:107], v[112:115], v[28:31]
	v_mfma_f32_16x16x32_bf16 v[80:83], v[96:99], v[120:123], v[80:83]
	v_mfma_f32_16x16x32_bf16 v[16:19], v[104:107], v[120:123], v[16:19]
	v_mfma_f32_16x16x32_bf16 v[76:79], v[96:99], v[160:163], v[76:79]
	v_mfma_f32_16x16x32_bf16 v[12:15], v[104:107], v[160:163], v[12:15]
	v_mfma_f32_16x16x32_bf16 v[84:87], v[96:99], v[168:171], v[84:87]
	v_mfma_f32_16x16x32_bf16 v[20:23], v[104:107], v[168:171], v[20:23]
	v_mfma_f32_16x16x32_bf16 v[92:95], v[100:103], v[116:119], v[92:95]
	v_mfma_f32_16x16x32_bf16 v[28:31], v[108:111], v[116:119], v[28:31]
	v_mfma_f32_16x16x32_bf16 v[80:83], v[100:103], v[124:127], v[80:83]
	v_mfma_f32_16x16x32_bf16 v[16:19], v[108:111], v[124:127], v[16:19]
	v_mfma_f32_16x16x32_bf16 v[76:79], v[100:103], v[164:167], v[76:79]
	v_mfma_f32_16x16x32_bf16 v[12:15], v[108:111], v[164:167], v[12:15]
	v_mfma_f32_16x16x32_bf16 v[84:87], v[100:103], v[172:175], v[84:87]
	v_mfma_f32_16x16x32_bf16 v[20:23], v[108:111], v[172:175], v[20:23]
	v_mfma_f32_16x16x32_bf16 v[88:91], v[180:183], v[112:115], v[88:91]
	v_mfma_f32_16x16x32_bf16 v[24:27], v[188:191], v[112:115], v[24:27]
	v_mfma_f32_16x16x32_bf16 v[68:71], v[180:183], v[120:123], v[68:71]
	v_mfma_f32_16x16x32_bf16 v[4:7], v[188:191], v[120:123], v[4:7]
	v_mfma_f32_16x16x32_bf16 v[64:67], v[180:183], v[160:163], v[64:67]
	v_mfma_f32_16x16x32_bf16 v[0:3], v[188:191], v[160:163], v[0:3]
	v_mfma_f32_16x16x32_bf16 v[72:75], v[180:183], v[168:171], v[72:75]
	v_mfma_f32_16x16x32_bf16 v[8:11], v[188:191], v[168:171], v[8:11]
	v_mfma_f32_16x16x32_bf16 v[88:91], v[184:187], v[116:119], v[88:91]
	v_mfma_f32_16x16x32_bf16 v[24:27], v[192:195], v[116:119], v[24:27]
	v_mfma_f32_16x16x32_bf16 v[68:71], v[184:187], v[124:127], v[68:71]
	v_mfma_f32_16x16x32_bf16 v[4:7], v[192:195], v[124:127], v[4:7]
	v_mfma_f32_16x16x32_bf16 v[64:67], v[184:187], v[164:167], v[64:67]
	v_mfma_f32_16x16x32_bf16 v[0:3], v[192:195], v[164:167], v[0:3]
	v_mfma_f32_16x16x32_bf16 v[72:75], v[184:187], v[172:175], v[72:75]
	v_mfma_f32_16x16x32_bf16 v[8:11], v[192:195], v[172:175], v[8:11]
	s_setprio 0
	s_add_i32 s79, s79, 2
	s_add_u32 s77, s77, 0x100
	s_addc_u32 s78, s78, 0
	s_cmp_gt_u32 s79, 13
	s_mov_b64 s[36:37], s[38:39]
	s_barrier
	s_cbranch_scc0 .LBB0_309
	s_lshl_b32 s36, s35, 7
	s_ashr_i32 s37, s36, 31
	s_lshl_b64 s[38:39], s[36:37], 2
	v_readfirstlane_b32 s99, v219
	v_and_b32_e32 v96, 15, v219
	v_and_b32_e32 v97, 3, v96
	v_mul_u32_u24_e32 v98, 0x5800, v97
	v_cmp_eq_u32_e32 vcc, 3, v97
	v_bfe_u32 v99, v96, 2, 1
	v_mul_u32_u24_e32 v99, 0x2c00, v99
	v_cndmask_b32_e64 v98, v98, 0, vcc
	v_add_u32_e32 v98, v98, v99
	v_bfe_u32 v99, v96, 3, 1
	v_lshl_add_u32 v98, v99, 4, v98
	v_add_u32_e32 v98, s38, v98
	v_cndmask_b32_e32 v100, v220, v222, vcc
	v_cndmask_b32_e32 v101, v221, v223, vcc
	v_add_co_u32_e32 v100, vcc, v100, v98
	s_nop 1
	v_addc_co_u32_e32 v101, vcc, 0, v101, vcc
	s_bitcmp1_b32 s99, 8
	s_cbranch_scc1 .Lcw309_skip
	global_load_dwordx4 v[108:111], v[100:101], off
;     __device__ __forceinline__ void operator()(AccRef acc, const Unit& u, int wr, int wc, int fr, int fq) const {
;     ...
;         if (fr == 15) {
; #pragma unroll
;             for (int ai = 0; ai < 2; ++ai)
; #pragma unroll
;                 for (int bj = 0; bj < 2; ++bj)
; #pragma unroll
;                     for (int n = 0; n < 2; ++n) { *(LAS f32x4*)(xch + ((ai * 2 + wr) * 2 + 0) * 256 + bj * 128 + clb + 4 * n) = acc[ai][bj][2][n]; *(LAS f32x4*)(xch + ((ai * 2 + wr) * 2 + 1) * 256 + bj * 128 + clb + 4 * n) = acc[ai][bj][3][n]; }
;         }
;         float* rawu = raw + (size_t)(u.pm * 22 + u.pn) * 1024;
;         if (wr == 0 && fr == 0) {
; #pragma unroll
;             for (int bj = 0; bj < 2; ++bj)
; #pragma unroll
;                 for (int n = 0; n < 2; ++n) { *(f32x4*)(rawu + 0 * 256 + bj * 128 + clb + 4 * n) = acc[0][bj][0][n]; *(f32x4*)(rawu + 1 * 256 + bj * 128 + clb + 4 * n) = acc[0][bj][1][n]; }
;         }
;         if (wr == 1 && fr == 15) {
; #pragma unroll
;             for (int bj = 0; bj < 2; ++bj)
; #pragma unroll
;                 for (int n = 0; n < 2; ++n) { *(f32x4*)(rawu + 2 * 256 + bj * 128 + clb + 4 * n) = acc[1][bj][2][n]; *(f32x4*)(rawu + 3 * 256 + bj * 128 + clb + 4 * n) = acc[1][bj][3][n]; }
;         }
;         asm volatile("s_waitcnt lgkmcnt(0)" ::: "memory"); __builtin_amdgcn_s_barrier(); __builtin_amdgcn_s_barrier(); asm volatile("" ::: "memory");
;         const int hc0 = 128 * u.pn + clb, row0 = u.pm * 256 + wr * 64 + 4 * fr;
; #pragma unroll
;         for (int n = 0; n < 2; ++n) {
;             const f32x4 w0v = cwv[n][0], w1v = cwv[n][1], w2v = cwv[n][2], bvv = cwv[n][3], w0g = cwv[n][4], w1g = cwv[n][5], w2g = cwv[n][6], bvg = cwv[n][7];
; #pragma unroll
;             for (int ai = 0; ai < 2; ++ai) {
;                 if (n == 0 && ai == 0) {
;                     asm volatile("" ::: "memory");
;                     const float* cv = cw + hc0 + 4; const float* cg = cv + FH; const float* bp = cb + hc0 + 4;
;                     cwv[1][0] = *(const f32x4*)(cv); cwv[1][1] = *(const f32x4*)(cv + F2); cwv[1][2] = *(const f32x4*)(cv + 2 * F2); cwv[1][3] = *(const f32x4*)(bp);
;                     cwv[1][4] = *(const f32x4*)(cg); cwv[1][5] = *(const f32x4*)(cg + F2); cwv[1][6] = *(const f32x4*)(cg + 2 * F2); cwv[1][7] = *(const f32x4*)(bp + FH);
;                     asm volatile("" ::: "memory"); }
.Lcw309_skip:
	s_and_saveexec_b64 s[38:39], s[8:9]
	s_cbranch_execz .LBB0_312
	ds_write_b128 v237, v[136:139]
	ds_write_b128 v237, v[148:151] offset:1024
	ds_write_b128 v237, v[40:43] offset:16
	ds_write_b128 v237, v[52:55] offset:1040
	ds_write_b128 v237, v[128:131] offset:512
	ds_write_b128 v237, v[140:143] offset:1536
	ds_write_b128 v237, v[32:35] offset:528
	ds_write_b128 v237, v[44:47] offset:1552
	ds_write_b128 v237, v[76:79] offset:4096
	ds_write_b128 v237, v[84:87] offset:5120
	ds_write_b128 v237, v[12:15] offset:4112
	ds_write_b128 v237, v[20:23] offset:5136
	ds_write_b128 v237, v[64:67] offset:4608
	ds_write_b128 v237, v[72:75] offset:5632
	ds_write_b128 v237, v[0:3] offset:4624
	ds_write_b128 v237, v[8:11] offset:5648
.LBB0_312:
	s_or_b64 exec, exec, s[38:39]
	s_mul_i32 s25, s34, 22
	s_add_i32 s38, s25, s35
	s_ashr_i32 s39, s38, 31
	s_lshl_b64 s[38:39], s[38:39], 12
	s_add_u32 s38, s64, s38
	s_addc_u32 s39, s65, s39
	v_lshlrev_b32_e32 v96, 2, v218
	v_or_b32_e32 v232, s36, v218
	v_ashrrev_i32_e32 v233, 31, v232
	v_lshlrev_b64 v[96:97], 2, v[232:233]
	v_lshl_add_u64 v[120:121], s[56:57], 0, v[96:97]
	v_add_co_u32_e32 v100, vcc, 0x5000, v120
	s_bitcmp1_b32 s99, 8
	s_cbranch_scc1 .Lcw309_nostage
	s_waitcnt vmcnt(0)
	v_and_b32_e32 v107, 0xff, v219
	v_lshlrev_b32_e32 v107, 4, v107
	v_add_u32_e32 v107, 0x22000, v107
	ds_write_b128 v107, v[108:111]
.Lcw309_nostage:
	s_waitcnt lgkmcnt(0)
	s_barrier
	s_nop 0
	v_addc_co_u32_e32 v101, vcc, 0, v121, vcc
	v_add_co_u32_e32 v104, vcc, 0xb000, v120
	s_barrier
	s_nop 0
	v_addc_co_u32_e32 v105, vcc, 0, v121, vcc
	v_add_co_u32_e32 v112, vcc, s49, v120
	v_lshl_add_u64 v[124:125], s[58:59], 0, v[96:97]
	s_nop 0
	v_addc_co_u32_e32 v113, vcc, 0, v121, vcc
	v_add_co_u32_e32 v116, vcc, 0x8000, v120
	s_nop 0
	s_nop 0
	v_addc_co_u32_e32 v117, vcc, 0, v121, vcc
	v_add_co_u32_e32 v120, vcc, 0xd000, v120
	s_nop 0
	s_nop 0
	v_addc_co_u32_e32 v121, vcc, 0, v121, vcc
	v_add_co_u32_e32 v124, vcc, 0x2000, v124
	s_nop 0
	s_nop 0
	v_addc_co_u32_e32 v125, vcc, 0, v125, vcc
	v_mov_b32_e32 v192, 0
	v_mov_b32_e32 v198, 0
	v_mov_b32_e32 v199, 0
	v_mov_b32_e32 v200, 0
	v_mov_b32_e32 v201, 0
	v_mov_b32_e32 v206, 0
	v_mov_b32_e32 v207, 0
	v_mov_b32_e32 v208, 0
	v_mov_b32_e32 v209, 0
	v_mov_b32_e32 v194, 0
	v_mov_b32_e32 v195, 0
	v_mov_b32_e32 v196, 0
	v_mov_b32_e32 v197, 0
	v_mov_b32_e32 v202, 0
	v_mov_b32_e32 v203, 0
	v_mov_b32_e32 v204, 0
	v_mov_b32_e32 v205, 0
	s_and_saveexec_b64 s[36:37], s[18:19]
	s_cbranch_execz .LBB0_318
	ds_read_b128 v[202:205], v238
	ds_read_b128 v[206:209], v238 offset:512
	ds_read_b128 v[194:197], v238 offset:1024
	ds_read_b128 v[198:201], v238 offset:1536
.LBB0_318:
	s_or_b64 exec, exec, s[36:37]
	s_waitcnt lgkmcnt(0)
	v_mov_b32_dpp v198, v140 row_shr:1 row_mask:0xf bank_mask:0xf
	v_mov_b32_dpp v199, v141 row_shr:1 row_mask:0xf bank_mask:0xf
	s_waitcnt vmcnt(8)
	v_and_b32_e32 v253, 0xf0, v219
	v_lshlrev_b32_e32 v253, 4, v253
	v_add_u32_e32 v253, 0x22000, v253
	ds_read_b128 v[160:163], v253
	ds_read_b128 v[164:167], v253 offset:16
	ds_read_b128 v[168:171], v253 offset:32
	ds_read_b128 v[172:175], v253 offset:48
	ds_read_b128 v[176:179], v253 offset:64
	ds_read_b128 v[180:183], v253 offset:80
	ds_read_b128 v[184:187], v253 offset:96
	ds_read_b128 v[188:191], v253 offset:112
	ds_read_b128 v[96:99], v253 offset:128
	ds_read_b128 v[100:103], v253 offset:144
	ds_read_b128 v[104:107], v253 offset:160
	ds_read_b128 v[108:111], v253 offset:176
	ds_read_b128 v[112:115], v253 offset:192
	ds_read_b128 v[116:119], v253 offset:208
	ds_read_b128 v[120:123], v253 offset:224
	ds_read_b128 v[124:127], v253 offset:240
	s_waitcnt lgkmcnt(0)
	v_lshlrev_b32_e32 v253, 2, v218
	s_and_saveexec_b64 s[40:41], s[10:11]
	s_cbranch_execz .LBB0_314
	global_store_dwordx4 v253, v[156:159], s[38:39]
	global_store_dwordx4 v253, v[144:147], s[38:39] offset:1024
	global_store_dwordx4 v253, v[60:63], s[38:39] offset:16
	global_store_dwordx4 v253, v[48:51], s[38:39] offset:1040
	global_store_dwordx4 v253, v[152:155], s[38:39] offset:512
	global_store_dwordx4 v253, v[132:135], s[38:39] offset:1536
	global_store_dwordx4 v253, v[56:59], s[38:39] offset:528
	global_store_dwordx4 v253, v[36:39], s[38:39] offset:1552

; #define PG8_STAGE(bufoff, gbase, voff) do { _Pragma("unroll") for (int _i = 0; _i < 2; ++_i) \
;         __builtin_amdgcn_global_load_lds((const unsigned*)((const char*)(gbase) + (voff)[_i]), (LAS unsigned*)(lds + (bufoff) + ldsw + _i * 8192), 16, 0, 0); } while (0)
; #define PG8_LDA(dst, b, h) do { _Pragma("unroll") for (int m = 0; m < 4; ++m) _Pragma("unroll") for (int k = 0; k < 2; ++k) dst[m][k] = *(const LAS bf16x8*)(lds + PG8_SA(b, h) + aoff + m * 2048 + k * 1024); } while (0)
; #define PG8_LDB(dst, b, h) do { _Pragma("unroll") for (int n = 0; n < 2; ++n) _Pragma("unroll") for (int k = 0; k < 2; ++k) dst[n][k] = *(const LAS bf16x8*)(lds + PG8_SB(b, h) + boff + n * 2048 + k * 1024); } while (0)
; #define PG8_MMA(ai, bj, At, Bt) do { __builtin_amdgcn_s_setprio(1); _Pragma("unroll") for (int m = 0; m < 4; ++m) _Pragma("unroll") for (int n = 0; n < 2; ++n) _Pragma("unroll") for (int k = 0; k < 2; ++k) \
;         acc[ai][bj][m][n] = __builtin_amdgcn_mfma_f32_16x16x32_bf16(Bt[n][k], At[m][k], acc[ai][bj][m][n], 0, 0, 0); __builtin_amdgcn_s_setprio(0); } while (0)
; #define PG8_WAIT_V(n) asm volatile("s_waitcnt vmcnt(" #n ")" ::: "memory")
; #define PG8_WAIT_L(n) asm volatile("s_waitcnt lgkmcnt(" #n ")" ::: "memory")
; #define PG8_BAR __builtin_amdgcn_s_barrier()
; #define PG8_SCHED __builtin_amdgcn_sched_barrier(0)
; template <class Epi>
; __device__ __forceinline__ void gemm_phase(LAS unsigned char* lds, const Gemm g, const StaticOrder& S, const Epi& E) {
;     ...
;             PG8_LDB(B0, 0, 0); PG8_SCHED; PG8_LDA(At, 0, 0); PG8_STAGE(PG8_SA(1, 1), a1 + hstepA, voffA);
;             PG8_WAIT_L(8); PG8_BAR; PG8_WAIT_L(0); PG8_MMA(0, 0, At, B0); PG8_BAR; PG8_SCHED;
;             PG8_LDB(B1, 0, 1); PG8_STAGE(PG8_SB(0, 0), b2, voffB);
;             PG8_BAR; PG8_WAIT_L(0); PG8_MMA(0, 1, At, B1); PG8_BAR;
;             PG8_LDA(At, 0, 1); PG8_STAGE(PG8_SA(0, 0), a2, voffA);
;             PG8_BAR; PG8_WAIT_L(0); PG8_MMA(1, 0, At, B0); PG8_BAR; PG8_SCHED;
;             PG8_STAGE(PG8_SB(0, 1), b2 + hstepB, voffB);
;             PG8_WAIT_V(6); PG8_BAR; PG8_MMA(1, 1, At, B1); PG8_BAR;
.LBB0_758:
	ds_read_b128 v[96:99], v243
	ds_read_b128 v[100:103], v243 offset:1024
	ds_read_b128 v[104:107], v243 offset:2048
	ds_read_b128 v[108:111], v243 offset:3072
	s_add_u32 s44, s42, 0x100
	s_addc_u32 s45, s43, 0
	s_cmp_eq_u32 s81, 12
	s_cselect_b32 s49, s35, s45
	s_cselect_b32 s48, s77, s44
	s_cselect_b32 s47, s31, s80
	s_cselect_b32 s46, s78, s79
	v_lshl_add_u64 v[176:177], s[42:43], 0, v[224:225]
	s_add_i32 m0, s9, 0xc000
	ds_read_b128 v[112:115], v244
	ds_read_b128 v[116:119], v244 offset:1024
	ds_read_b128 v[120:123], v244 offset:2048
	ds_read_b128 v[124:127], v244 offset:3072
	ds_read_b128 v[160:163], v244 offset:4096
	ds_read_b128 v[164:167], v244 offset:5120
	ds_read_b128 v[168:171], v244 offset:6144
	ds_read_b128 v[172:175], v244 offset:7168
	global_load_lds_dwordx4 v[176:177], off
	v_lshl_add_u64 v[176:177], s[42:43], 0, v[226:227]
	s_add_i32 m0, s9, 0xe000
	s_nop 0
	global_load_lds_dwordx4 v[176:177], off
	ds_read_b128 v[176:179], v245
	ds_read_b128 v[180:183], v245 offset:1024
	ds_read_b128 v[184:187], v245 offset:2048
	ds_read_b128 v[188:191], v245 offset:3072
	s_waitcnt lgkmcnt(0)
	s_barrier
	s_setprio 1
	v_mfma_f32_16x16x32_bf16 v[156:159], v[96:99], v[112:115], v[156:159]
	v_mfma_f32_16x16x32_bf16 v[60:63], v[104:107], v[112:115], v[60:63]
	v_mfma_f32_16x16x32_bf16 v[144:147], v[96:99], v[120:123], v[144:147]
	v_mfma_f32_16x16x32_bf16 v[48:51], v[104:107], v[120:123], v[48:51]
	v_mfma_f32_16x16x32_bf16 v[136:139], v[96:99], v[160:163], v[136:139]
	v_mfma_f32_16x16x32_bf16 v[40:43], v[104:107], v[160:163], v[40:43]
	v_mfma_f32_16x16x32_bf16 v[148:151], v[96:99], v[168:171], v[148:151]
	v_mfma_f32_16x16x32_bf16 v[52:55], v[104:107], v[168:171], v[52:55]
	v_mfma_f32_16x16x32_bf16 v[156:159], v[100:103], v[116:119], v[156:159]
	v_mfma_f32_16x16x32_bf16 v[60:63], v[108:111], v[116:119], v[60:63]
	v_mfma_f32_16x16x32_bf16 v[144:147], v[100:103], v[124:127], v[144:147]
	v_mfma_f32_16x16x32_bf16 v[48:51], v[108:111], v[124:127], v[48:51]
	v_mfma_f32_16x16x32_bf16 v[136:139], v[100:103], v[164:167], v[136:139]
	v_mfma_f32_16x16x32_bf16 v[40:43], v[108:111], v[164:167], v[40:43]
	v_mfma_f32_16x16x32_bf16 v[148:151], v[100:103], v[172:175], v[148:151]
	v_mfma_f32_16x16x32_bf16 v[52:55], v[108:111], v[172:175], v[52:55]
	v_mfma_f32_16x16x32_bf16 v[152:155], v[176:179], v[112:115], v[152:155]
	v_mfma_f32_16x16x32_bf16 v[56:59], v[184:187], v[112:115], v[56:59]
	v_mfma_f32_16x16x32_bf16 v[36:39], v[184:187], v[120:123], v[36:39]
	v_mfma_f32_16x16x32_bf16 v[32:35], v[184:187], v[160:163], v[32:35]
	v_mfma_f32_16x16x32_bf16 v[44:47], v[184:187], v[168:171], v[44:47]
	v_mfma_f32_16x16x32_bf16 v[152:155], v[180:183], v[116:119], v[152:155]
	v_mfma_f32_16x16x32_bf16 v[56:59], v[188:191], v[116:119], v[56:59]
	v_mfma_f32_16x16x32_bf16 v[112:115], v[176:179], v[120:123], v[132:135]
	v_mfma_f32_16x16x32_bf16 v[36:39], v[188:191], v[124:127], v[36:39]
	v_mfma_f32_16x16x32_bf16 v[116:119], v[176:179], v[160:163], v[128:131]
	v_mfma_f32_16x16x32_bf16 v[32:35], v[188:191], v[164:167], v[32:35]
	v_mfma_f32_16x16x32_bf16 v[120:123], v[176:179], v[168:171], v[140:143]
	v_mfma_f32_16x16x32_bf16 v[44:47], v[188:191], v[172:175], v[44:47]
	v_mfma_f32_16x16x32_bf16 v[112:115], v[180:183], v[124:127], v[112:115]
	v_mfma_f32_16x16x32_bf16 v[116:119], v[180:183], v[164:167], v[116:119]
	v_mfma_f32_16x16x32_bf16 v[120:123], v[180:183], v[172:175], v[120:123]
	s_setprio 0
	s_barrier
	s_nop 1
	ds_read_b128 v[124:127], v244 offset:16384
	ds_read_b128 v[128:131], v244 offset:17408
	ds_read_b128 v[132:135], v244 offset:18432
	ds_read_b128 v[140:143], v244 offset:19456
	ds_read_b128 v[160:163], v244 offset:20480
	ds_read_b128 v[164:167], v244 offset:21504
	ds_read_b128 v[168:171], v244 offset:22528
	ds_read_b128 v[172:175], v244 offset:23552
	s_add_i32 s42, s74, s7
	v_lshl_add_u64 v[196:197], s[46:47], 0, v[214:215]
	s_mov_b32 m0, s42
	s_nop 0
	global_load_lds_dwordx4 v[196:197], off
	v_lshl_add_u64 v[198:199], s[46:47], 0, v[210:211]
	s_add_i32 m0, s42, 0x2000
	s_nop 0
	global_load_lds_dwordx4 v[198:199], off
	s_mov_b32 m0, s9
	v_lshl_add_u64 v[200:201], s[48:49], 0, v[216:217]
	global_load_lds_dwordx4 v[200:201], off
	v_lshl_add_u64 v[202:203], s[48:49], 0, v[212:213]
	s_mov_b32 m0, s63
	s_nop 0
	global_load_lds_dwordx4 v[202:203], off
	s_add_u32 s42, s46, 0x40000
	s_addc_u32 s43, s47, 0
	s_add_i32 s82, s75, s7
	v_lshl_add_u64 v[254:255], s[42:43], 0, v[214:215]
	s_mov_b32 m0, s82
	s_nop 0
	global_load_lds_dwordx4 v[254:255], off
	v_lshl_add_u64 v[254:255], s[42:43], 0, v[210:211]
	s_add_i32 m0, s82, 0x2000
	s_nop 0
	global_load_lds_dwordx4 v[254:255], off
	s_waitcnt vmcnt(6)
	s_waitcnt lgkmcnt(0)
	s_barrier
; #define PG8_STAGE(bufoff, gbase, voff) do { _Pragma("unroll") for (int _i = 0; _i < 2; ++_i) \
;         __builtin_amdgcn_global_load_lds((const unsigned*)((const char*)(gbase) + (voff)[_i]), (LAS unsigned*)(lds + (bufoff) + ldsw + _i * 8192), 16, 0, 0); } while (0)
; #define PG8_LDA(dst, b, h) do { _Pragma("unroll") for (int m = 0; m < 4; ++m) _Pragma("unroll") for (int k = 0; k < 2; ++k) dst[m][k] = *(const LAS bf16x8*)(lds + PG8_SA(b, h) + aoff + m * 2048 + k * 1024); } while (0)
; #define PG8_LDB(dst, b, h) do { _Pragma("unroll") for (int n = 0; n < 2; ++n) _Pragma("unroll") for (int k = 0; k < 2; ++k) dst[n][k] = *(const LAS bf16x8*)(lds + PG8_SB(b, h) + boff + n * 2048 + k * 1024); } while (0)
; #define PG8_MMA(ai, bj, At, Bt) do { __builtin_amdgcn_s_setprio(1); _Pragma("unroll") for (int m = 0; m < 4; ++m) _Pragma("unroll") for (int n = 0; n < 2; ++n) _Pragma("unroll") for (int k = 0; k < 2; ++k) \
;         acc[ai][bj][m][n] = __builtin_amdgcn_mfma_f32_16x16x32_bf16(Bt[n][k], At[m][k], acc[ai][bj][m][n], 0, 0, 0); __builtin_amdgcn_s_setprio(0); } while (0)
; #define PG8_WAIT_V(n) asm volatile("s_waitcnt vmcnt(" #n ")" ::: "memory")
; #define PG8_WAIT_L(n) asm volatile("s_waitcnt lgkmcnt(" #n ")" ::: "memory")
; #define PG8_BAR __builtin_amdgcn_s_barrier()
; #define PG8_SCHED __builtin_amdgcn_sched_barrier(0)
; template <class Epi>
; __device__ __forceinline__ void gemm_phase(LAS unsigned char* lds, const Gemm g, const StaticOrder& S, const Epi& E) {
;     ...
;             PG8_LDB(B1, 0, 1); PG8_STAGE(PG8_SB(0, 0), b2, voffB);
;             PG8_BAR; PG8_WAIT_L(0); PG8_MMA(0, 1, At, B1); PG8_BAR;
;             PG8_LDA(At, 0, 1); PG8_STAGE(PG8_SA(0, 0), a2, voffA);
;             PG8_BAR; PG8_WAIT_L(0); PG8_MMA(1, 0, At, B0); PG8_BAR; PG8_SCHED;
;             PG8_STAGE(PG8_SB(0, 1), b2 + hstepB, voffB);
;             PG8_WAIT_V(6); PG8_BAR; PG8_MMA(1, 1, At, B1); PG8_BAR;
;             PG8_LDB(B0, 1, 0); PG8_SCHED; PG8_LDA(At, 1, 0); PG8_STAGE(PG8_SA(0, 1), a2 + hstepA, voffA);
;             PG8_WAIT_L(8); PG8_BAR; PG8_WAIT_L(0); PG8_MMA(0, 0, At, B0); PG8_BAR; PG8_SCHED;
;             PG8_LDB(B1, 1, 1); PG8_STAGE(PG8_SB(1, 0), b3, voffB);
;             PG8_BAR; PG8_WAIT_L(0); PG8_MMA(0, 1, At, B1); PG8_BAR;
;             PG8_LDA(At, 1, 1); PG8_STAGE(PG8_SA(1, 0), a3, voffA);
;             PG8_BAR; PG8_WAIT_L(0); PG8_MMA(1, 0, At, B0); PG8_BAR; PG8_SCHED;
	s_setprio 1
	v_mfma_f32_16x16x32_bf16 v[92:95], v[96:99], v[124:127], v[92:95]
	v_mfma_f32_16x16x32_bf16 v[28:31], v[104:107], v[124:127], v[28:31]
	v_mfma_f32_16x16x32_bf16 v[80:83], v[96:99], v[132:135], v[80:83]
	v_mfma_f32_16x16x32_bf16 v[16:19], v[104:107], v[132:135], v[16:19]
	v_mfma_f32_16x16x32_bf16 v[76:79], v[96:99], v[160:163], v[76:79]
	v_mfma_f32_16x16x32_bf16 v[12:15], v[104:107], v[160:163], v[12:15]
	v_mfma_f32_16x16x32_bf16 v[84:87], v[96:99], v[168:171], v[84:87]
	v_mfma_f32_16x16x32_bf16 v[20:23], v[104:107], v[168:171], v[20:23]
	v_mfma_f32_16x16x32_bf16 v[92:95], v[100:103], v[128:131], v[92:95]
	v_mfma_f32_16x16x32_bf16 v[28:31], v[108:111], v[128:131], v[28:31]
	v_mfma_f32_16x16x32_bf16 v[80:83], v[100:103], v[140:143], v[80:83]
	v_mfma_f32_16x16x32_bf16 v[16:19], v[108:111], v[140:143], v[16:19]
	v_mfma_f32_16x16x32_bf16 v[76:79], v[100:103], v[164:167], v[76:79]
	v_mfma_f32_16x16x32_bf16 v[12:15], v[108:111], v[164:167], v[12:15]
	v_mfma_f32_16x16x32_bf16 v[84:87], v[100:103], v[172:175], v[84:87]
	v_mfma_f32_16x16x32_bf16 v[20:23], v[108:111], v[172:175], v[20:23]
	v_mfma_f32_16x16x32_bf16 v[88:91], v[176:179], v[124:127], v[88:91]
	v_mfma_f32_16x16x32_bf16 v[24:27], v[184:187], v[124:127], v[24:27]
	v_mfma_f32_16x16x32_bf16 v[68:71], v[176:179], v[132:135], v[68:71]
	v_mfma_f32_16x16x32_bf16 v[4:7], v[184:187], v[132:135], v[4:7]
	v_mfma_f32_16x16x32_bf16 v[64:67], v[176:179], v[160:163], v[64:67]
	v_mfma_f32_16x16x32_bf16 v[0:3], v[184:187], v[160:163], v[0:3]
	v_mfma_f32_16x16x32_bf16 v[72:75], v[176:179], v[168:171], v[72:75]
	v_mfma_f32_16x16x32_bf16 v[8:11], v[184:187], v[168:171], v[8:11]
	v_mfma_f32_16x16x32_bf16 v[88:91], v[180:183], v[128:131], v[88:91]
	v_mfma_f32_16x16x32_bf16 v[24:27], v[188:191], v[128:131], v[24:27]
	v_mfma_f32_16x16x32_bf16 v[68:71], v[180:183], v[140:143], v[68:71]
	v_mfma_f32_16x16x32_bf16 v[4:7], v[188:191], v[140:143], v[4:7]
	v_mfma_f32_16x16x32_bf16 v[64:67], v[180:183], v[164:167], v[64:67]
	v_mfma_f32_16x16x32_bf16 v[0:3], v[188:191], v[164:167], v[0:3]
	v_mfma_f32_16x16x32_bf16 v[72:75], v[180:183], v[172:175], v[72:75]
	v_mfma_f32_16x16x32_bf16 v[8:11], v[188:191], v[172:175], v[8:11]
	s_setprio 0
	s_add_i32 s82, 0, 0x18000
	v_add_u32_e32 v108, s82, v235
	s_barrier
	ds_read_b128 v[96:99], v108
	ds_read_b128 v[100:103], v108 offset:1024
	ds_read_b128 v[104:107], v108 offset:2048
	ds_read_b128 v[108:111], v108 offset:3072
	s_add_u32 s42, s48, 0x40000
	s_addc_u32 s43, s49, 0
	s_mov_b32 m0, s68
	v_lshl_add_u64 v[132:133], s[42:43], 0, v[216:217]
	ds_read_b128 v[124:127], v244 offset:32768
	ds_read_b128 v[128:131], v244 offset:33792
	ds_read_b128 v[140:143], v244 offset:34816
	ds_read_b128 v[160:163], v244 offset:35840
	ds_read_b128 v[164:167], v244 offset:36864
	ds_read_b128 v[168:171], v244 offset:37888
	ds_read_b128 v[172:175], v244 offset:38912
	ds_read_b128 v[176:179], v244 offset:39936
	global_load_lds_dwordx4 v[132:133], off
	v_lshl_add_u64 v[132:133], s[42:43], 0, v[212:213]
	s_mov_b32 m0, s69
	s_nop 0
	global_load_lds_dwordx4 v[132:133], off
	s_add_i32 s48, 0, 0x1c000
	v_add_u32_e32 v132, s48, v235
	ds_read_b128 v[180:183], v132
	ds_read_b128 v[184:187], v132 offset:1024
	ds_read_b128 v[188:191], v132 offset:2048
	ds_read_b128 v[192:195], v132 offset:3072
	s_waitcnt lgkmcnt(0)
	s_barrier
	s_setprio 1
	v_mfma_f32_16x16x32_bf16 v[132:135], v[96:99], v[124:127], v[156:159]
	v_mfma_f32_16x16x32_bf16 v[156:159], v[100:103], v[128:131], v[132:135]
	v_mfma_f32_16x16x32_bf16 v[132:135], v[96:99], v[140:143], v[144:147]
	v_mfma_f32_16x16x32_bf16 v[144:147], v[100:103], v[160:163], v[132:135]
	v_mfma_f32_16x16x32_bf16 v[132:135], v[96:99], v[164:167], v[136:139]
	v_mfma_f32_16x16x32_bf16 v[60:63], v[104:107], v[124:127], v[60:63]
	v_mfma_f32_16x16x32_bf16 v[48:51], v[104:107], v[140:143], v[48:51]
	v_mfma_f32_16x16x32_bf16 v[136:139], v[100:103], v[168:171], v[132:135]
	v_mfma_f32_16x16x32_bf16 v[40:43], v[104:107], v[164:167], v[40:43]
	v_mfma_f32_16x16x32_bf16 v[132:135], v[96:99], v[172:175], v[148:151]
	v_mfma_f32_16x16x32_bf16 v[52:55], v[104:107], v[172:175], v[52:55]
	v_mfma_f32_16x16x32_bf16 v[60:63], v[108:111], v[128:131], v[60:63]
	v_mfma_f32_16x16x32_bf16 v[48:51], v[108:111], v[160:163], v[48:51]
	v_mfma_f32_16x16x32_bf16 v[40:43], v[108:111], v[168:171], v[40:43]
	v_mfma_f32_16x16x32_bf16 v[148:151], v[100:103], v[176:179], v[132:135]
	v_mfma_f32_16x16x32_bf16 v[52:55], v[108:111], v[176:179], v[52:55]
	v_mfma_f32_16x16x32_bf16 v[132:135], v[180:183], v[124:127], v[152:155]
	v_mfma_f32_16x16x32_bf16 v[112:115], v[180:183], v[140:143], v[112:115]
	v_mfma_f32_16x16x32_bf16 v[152:155], v[184:187], v[128:131], v[132:135]
	v_mfma_f32_16x16x32_bf16 v[56:59], v[188:191], v[124:127], v[56:59]
	v_mfma_f32_16x16x32_bf16 v[132:135], v[184:187], v[160:163], v[112:115]
	v_mfma_f32_16x16x32_bf16 v[112:115], v[180:183], v[164:167], v[116:119]
	v_mfma_f32_16x16x32_bf16 v[56:59], v[192:195], v[128:131], v[56:59]
	v_mfma_f32_16x16x32_bf16 v[36:39], v[188:191], v[140:143], v[36:39]
	v_mfma_f32_16x16x32_bf16 v[128:131], v[184:187], v[168:171], v[112:115]
	v_mfma_f32_16x16x32_bf16 v[32:35], v[188:191], v[164:167], v[32:35]
	v_mfma_f32_16x16x32_bf16 v[112:115], v[180:183], v[172:175], v[120:123]
	v_mfma_f32_16x16x32_bf16 v[44:47], v[188:191], v[172:175], v[44:47]
	v_mfma_f32_16x16x32_bf16 v[36:39], v[192:195], v[160:163], v[36:39]
	v_mfma_f32_16x16x32_bf16 v[32:35], v[192:195], v[168:171], v[32:35]
	v_mfma_f32_16x16x32_bf16 v[140:143], v[184:187], v[176:179], v[112:115]
	v_mfma_f32_16x16x32_bf16 v[44:47], v[192:195], v[176:179], v[44:47]
	s_setprio 0
	s_barrier
; #define PG8_STAGE(bufoff, gbase, voff) do { _Pragma("unroll") for (int _i = 0; _i < 2; ++_i) \
;         __builtin_amdgcn_global_load_lds((const unsigned*)((const char*)(gbase) + (voff)[_i]), (LAS unsigned*)(lds + (bufoff) + ldsw + _i * 8192), 16, 0, 0); } while (0)
; #define PG8_LDA(dst, b, h) do { _Pragma("unroll") for (int m = 0; m < 4; ++m) _Pragma("unroll") for (int k = 0; k < 2; ++k) dst[m][k] = *(const LAS bf16x8*)(lds + PG8_SA(b, h) + aoff + m * 2048 + k * 1024); } while (0)
; #define PG8_LDB(dst, b, h) do { _Pragma("unroll") for (int n = 0; n < 2; ++n) _Pragma("unroll") for (int k = 0; k < 2; ++k) dst[n][k] = *(const LAS bf16x8*)(lds + PG8_SB(b, h) + boff + n * 2048 + k * 1024); } while (0)
; #define PG8_MMA(ai, bj, At, Bt) do { __builtin_amdgcn_s_setprio(1); _Pragma("unroll") for (int m = 0; m < 4; ++m) _Pragma("unroll") for (int n = 0; n < 2; ++n) _Pragma("unroll") for (int k = 0; k < 2; ++k) \
;         acc[ai][bj][m][n] = __builtin_amdgcn_mfma_f32_16x16x32_bf16(Bt[n][k], At[m][k], acc[ai][bj][m][n], 0, 0, 0); __builtin_amdgcn_s_setprio(0); } while (0)
; #define PG8_WAIT_V(n) asm volatile("s_waitcnt vmcnt(" #n ")" ::: "memory")
; #define PG8_WAIT_L(n) asm volatile("s_waitcnt lgkmcnt(" #n ")" ::: "memory")
; template <class Epi>
; __device__ __forceinline__ void gemm_phase(LAS unsigned char* lds, const Gemm g, const StaticOrder& S, const Epi& E) {
;     ...
;             PG8_LDB(B1, 1, 1); PG8_STAGE(PG8_SB(1, 0), b3, voffB);
;             PG8_BAR; PG8_WAIT_L(0); PG8_MMA(0, 1, At, B1); PG8_BAR;
;             PG8_LDA(At, 1, 1); PG8_STAGE(PG8_SA(1, 0), a3, voffA);
;             PG8_BAR; PG8_WAIT_L(0); PG8_MMA(1, 0, At, B0); PG8_BAR; PG8_SCHED;
;             PG8_STAGE(PG8_SB(1, 1), b3 + hstepB, voffB);
;             PG8_WAIT_V(6); PG8_BAR; PG8_MMA(1, 1, At, B1); PG8_BAR;
;     __device__ __forceinline__ void operator()(AccRef acc, const Unit& u, int wr, int wc, int fr, int fq) const {
;     ...
;         f32x4 cwv[2][8];
;         { const float* cv = cw + 128 * u.pn + clb; const float* cg = cv + FH; const float* bp = cb + 128 * u.pn + clb;
;           cwv[0][0] = *(const f32x4*)(cv); cwv[0][1] = *(const f32x4*)(cv + F2); cwv[0][2] = *(const f32x4*)(cv + 2 * F2); cwv[0][3] = *(const f32x4*)(bp);
;           cwv[0][4] = *(const f32x4*)(cg); cwv[0][5] = *(const f32x4*)(cg + F2); cwv[0][6] = *(const f32x4*)(cg + 2 * F2); cwv[0][7] = *(const f32x4*)(bp + FH); }
	s_nop 1
	ds_read_b128 v[112:115], v244 offset:49152
	ds_read_b128 v[116:119], v244 offset:50176
	ds_read_b128 v[120:123], v244 offset:51200
	ds_read_b128 v[124:127], v244 offset:52224
	ds_read_b128 v[160:163], v244 offset:53248
	ds_read_b128 v[164:167], v244 offset:54272
	ds_read_b128 v[168:171], v244 offset:55296
	ds_read_b128 v[172:175], v244 offset:56320
	s_add_i32 s42, s82, s7
	v_lshl_add_u64 v[254:255], v[196:197], 0, s[20:21]
	s_mov_b32 m0, s42
	s_nop 0
	global_load_lds_dwordx4 v[254:255], off
	v_lshl_add_u64 v[254:255], v[198:199], 0, s[20:21]
	s_add_i32 m0, s42, 0x2000
	s_nop 0
	global_load_lds_dwordx4 v[254:255], off
	s_mov_b32 m0, s72
	v_lshl_add_u64 v[254:255], v[200:201], 0, s[20:21]
	global_load_lds_dwordx4 v[254:255], off
	v_lshl_add_u64 v[254:255], v[202:203], 0, s[20:21]
	s_mov_b32 m0, s73
	s_nop 0
	global_load_lds_dwordx4 v[254:255], off
	s_add_u32 s42, s46, 0x40080
	s_addc_u32 s43, s47, 0
	s_add_i32 s46, s48, s7
	v_lshl_add_u64 v[254:255], s[42:43], 0, v[214:215]
	s_mov_b32 m0, s46
	s_nop 0
	global_load_lds_dwordx4 v[254:255], off
	v_lshl_add_u64 v[254:255], s[42:43], 0, v[210:211]
	s_add_i32 m0, s46, 0x2000
	s_nop 0
	global_load_lds_dwordx4 v[254:255], off
	s_waitcnt vmcnt(6)
	s_waitcnt lgkmcnt(0)
	s_barrier
	s_setprio 1
	v_mfma_f32_16x16x32_bf16 v[92:95], v[96:99], v[112:115], v[92:95]
	v_mfma_f32_16x16x32_bf16 v[28:31], v[104:107], v[112:115], v[28:31]
	v_mfma_f32_16x16x32_bf16 v[80:83], v[96:99], v[120:123], v[80:83]
	v_mfma_f32_16x16x32_bf16 v[16:19], v[104:107], v[120:123], v[16:19]
	v_mfma_f32_16x16x32_bf16 v[76:79], v[96:99], v[160:163], v[76:79]
	v_mfma_f32_16x16x32_bf16 v[12:15], v[104:107], v[160:163], v[12:15]
	v_mfma_f32_16x16x32_bf16 v[84:87], v[96:99], v[168:171], v[84:87]
	v_mfma_f32_16x16x32_bf16 v[20:23], v[104:107], v[168:171], v[20:23]
	v_mfma_f32_16x16x32_bf16 v[92:95], v[100:103], v[116:119], v[92:95]
	v_mfma_f32_16x16x32_bf16 v[28:31], v[108:111], v[116:119], v[28:31]
	v_mfma_f32_16x16x32_bf16 v[80:83], v[100:103], v[124:127], v[80:83]
	v_mfma_f32_16x16x32_bf16 v[16:19], v[108:111], v[124:127], v[16:19]
	v_mfma_f32_16x16x32_bf16 v[76:79], v[100:103], v[164:167], v[76:79]
	v_mfma_f32_16x16x32_bf16 v[12:15], v[108:111], v[164:167], v[12:15]
	v_mfma_f32_16x16x32_bf16 v[84:87], v[100:103], v[172:175], v[84:87]
	v_mfma_f32_16x16x32_bf16 v[20:23], v[108:111], v[172:175], v[20:23]
	v_mfma_f32_16x16x32_bf16 v[88:91], v[180:183], v[112:115], v[88:91]
	v_mfma_f32_16x16x32_bf16 v[24:27], v[188:191], v[112:115], v[24:27]
	v_mfma_f32_16x16x32_bf16 v[68:71], v[180:183], v[120:123], v[68:71]
	v_mfma_f32_16x16x32_bf16 v[4:7], v[188:191], v[120:123], v[4:7]
	v_mfma_f32_16x16x32_bf16 v[64:67], v[180:183], v[160:163], v[64:67]
	v_mfma_f32_16x16x32_bf16 v[0:3], v[188:191], v[160:163], v[0:3]
	v_mfma_f32_16x16x32_bf16 v[72:75], v[180:183], v[168:171], v[72:75]
	v_mfma_f32_16x16x32_bf16 v[8:11], v[188:191], v[168:171], v[8:11]
	v_mfma_f32_16x16x32_bf16 v[88:91], v[184:187], v[116:119], v[88:91]
	v_mfma_f32_16x16x32_bf16 v[24:27], v[192:195], v[116:119], v[24:27]
	v_mfma_f32_16x16x32_bf16 v[68:71], v[184:187], v[124:127], v[68:71]
	v_mfma_f32_16x16x32_bf16 v[4:7], v[192:195], v[124:127], v[4:7]
	v_mfma_f32_16x16x32_bf16 v[64:67], v[184:187], v[164:167], v[64:67]
	v_mfma_f32_16x16x32_bf16 v[0:3], v[192:195], v[164:167], v[0:3]
	v_mfma_f32_16x16x32_bf16 v[72:75], v[184:187], v[172:175], v[72:75]
	v_mfma_f32_16x16x32_bf16 v[8:11], v[192:195], v[172:175], v[8:11]
	s_setprio 0
	s_add_i32 s81, s81, 2
	s_add_u32 s79, s79, 0x100
	s_addc_u32 s80, s80, 0
	s_cmp_gt_u32 s81, 13
	s_mov_b64 s[42:43], s[44:45]
	s_barrier
	s_cbranch_scc0 .LBB0_758
	s_lshl_b32 s42, s41, 7
	s_ashr_i32 s43, s42, 31
	s_lshl_b64 s[44:45], s[42:43], 2
	v_readfirstlane_b32 s99, v219
	v_and_b32_e32 v96, 15, v219
	v_and_b32_e32 v97, 3, v96
	v_mul_u32_u24_e32 v98, 0x5800, v97
	v_cmp_eq_u32_e32 vcc, 3, v97
	v_bfe_u32 v99, v96, 2, 1
	v_mul_u32_u24_e32 v99, 0x2c00, v99
	v_cndmask_b32_e64 v98, v98, 0, vcc
	v_add_u32_e32 v98, v98, v99
	v_bfe_u32 v99, v96, 3, 1
	v_lshl_add_u32 v98, v99, 4, v98
	v_add_u32_e32 v98, s44, v98
	v_cndmask_b32_e32 v100, v220, v222, vcc
	v_cndmask_b32_e32 v101, v221, v223, vcc
	v_add_co_u32_e32 v100, vcc, v100, v98
	s_nop 1
	v_addc_co_u32_e32 v101, vcc, 0, v101, vcc
	s_bitcmp1_b32 s99, 8
	s_cbranch_scc1 .Lcw758_skip
	global_load_dwordx4 v[108:111], v[100:101], off
;     __device__ __forceinline__ void operator()(AccRef acc, const Unit& u, int wr, int wc, int fr, int fq) const {
;         const int clb = 32 * wc + 8 * fq;
;         f32x4 cwv[2][8];
;         { const float* cv = cw + 128 * u.pn + clb; const float* cg = cv + FH; const float* bp = cb + 128 * u.pn + clb;
;           cwv[0][0] = *(const f32x4*)(cv); cwv[0][1] = *(const f32x4*)(cv + F2); cwv[0][2] = *(const f32x4*)(cv + 2 * F2); cwv[0][3] = *(const f32x4*)(bp);
;           cwv[0][4] = *(const f32x4*)(cg); cwv[0][5] = *(const f32x4*)(cg + F2); cwv[0][6] = *(const f32x4*)(cg + 2 * F2); cwv[0][7] = *(const f32x4*)(bp + FH); }
;         if (fr == 15) {
; #pragma unroll
;             for (int ai = 0; ai < 2; ++ai)
; #pragma unroll
;                 for (int bj = 0; bj < 2; ++bj)
; #pragma unroll
;                     for (int n = 0; n < 2; ++n) { *(LAS f32x4*)(xch + ((ai * 2 + wr) * 2 + 0) * 256 + bj * 128 + clb + 4 * n) = acc[ai][bj][2][n]; *(LAS f32x4*)(xch + ((ai * 2 + wr) * 2 + 1) * 256 + bj * 128 + clb + 4 * n) = acc[ai][bj][3][n]; }
;         }
;         float* rawu = raw + (size_t)(u.pm * 22 + u.pn) * 1024;
;         if (wr == 0 && fr == 0) {
; #pragma unroll
;             for (int bj = 0; bj < 2; ++bj)
; #pragma unroll
;                 for (int n = 0; n < 2; ++n) { *(f32x4*)(rawu + 0 * 256 + bj * 128 + clb + 4 * n) = acc[0][bj][0][n]; *(f32x4*)(rawu + 1 * 256 + bj * 128 + clb + 4 * n) = acc[0][bj][1][n]; }
;         }
;         if (wr == 1 && fr == 15) {
; #pragma unroll
;             for (int bj = 0; bj < 2; ++bj)
; #pragma unroll
;                 for (int n = 0; n < 2; ++n) { *(f32x4*)(rawu + 2 * 256 + bj * 128 + clb + 4 * n) = acc[1][bj][2][n]; *(f32x4*)(rawu + 3 * 256 + bj * 128 + clb + 4 * n) = acc[1][bj][3][n]; }
;         }
;         asm volatile("s_waitcnt lgkmcnt(0)" ::: "memory"); __builtin_amdgcn_s_barrier(); __builtin_amdgcn_s_barrier(); asm volatile("" ::: "memory");
;         const int hc0 = 128 * u.pn + clb, row0 = u.pm * 256 + wr * 64 + 4 * fr;
; #pragma unroll
;         for (int n = 0; n < 2; ++n) {
;             const f32x4 w0v = cwv[n][0], w1v = cwv[n][1], w2v = cwv[n][2], bvv = cwv[n][3], w0g = cwv[n][4], w1g = cwv[n][5], w2g = cwv[n][6], bvg = cwv[n][7];
; #pragma unroll
;             for (int ai = 0; ai < 2; ++ai) {
;                 if (n == 0 && ai == 0) {
;                     asm volatile("" ::: "memory");
.Lcw758_skip:
	s_and_saveexec_b64 s[44:45], s[10:11]
	s_cbranch_execz .LBB0_761
	ds_write_b128 v237, v[136:139]
	ds_write_b128 v237, v[148:151] offset:1024
	ds_write_b128 v237, v[40:43] offset:16
	ds_write_b128 v237, v[52:55] offset:1040
	ds_write_b128 v237, v[128:131] offset:512
	ds_write_b128 v237, v[140:143] offset:1536
	ds_write_b128 v237, v[32:35] offset:528
	ds_write_b128 v237, v[44:47] offset:1552
	ds_write_b128 v237, v[76:79] offset:4096
	ds_write_b128 v237, v[84:87] offset:5120
	ds_write_b128 v237, v[12:15] offset:4112
	ds_write_b128 v237, v[20:23] offset:5136
	ds_write_b128 v237, v[64:67] offset:4608
	ds_write_b128 v237, v[72:75] offset:5632
	ds_write_b128 v237, v[0:3] offset:4624
	ds_write_b128 v237, v[8:11] offset:5648
.LBB0_761:
	s_or_b64 exec, exec, s[44:45]
	s_mul_i32 s31, s40, 22
	s_add_i32 s44, s31, s41
	s_ashr_i32 s45, s44, 31
	s_lshl_b64 s[44:45], s[44:45], 12
	s_add_u32 s44, s64, s44
	s_addc_u32 s45, s65, s45
	v_lshlrev_b32_e32 v96, 2, v218
	v_or_b32_e32 v232, s42, v218
	v_ashrrev_i32_e32 v233, 31, v232
	v_lshlrev_b64 v[96:97], 2, v[232:233]
	v_lshl_add_u64 v[120:121], s[18:19], 0, v[96:97]
	v_add_co_u32_e32 v100, vcc, 0x5000, v120
	s_bitcmp1_b32 s99, 8
	s_cbranch_scc1 .Lcw758_nostage
	s_waitcnt vmcnt(0)
	v_and_b32_e32 v107, 0xff, v219
	v_lshlrev_b32_e32 v107, 4, v107
	v_add_u32_e32 v107, 0x22000, v107
	ds_write_b128 v107, v[108:111]
.Lcw758_nostage:
	s_waitcnt lgkmcnt(0)
	s_barrier
	s_nop 0
	v_addc_co_u32_e32 v101, vcc, 0, v121, vcc
	v_add_co_u32_e32 v104, vcc, 0xb000, v120
	s_barrier
	s_nop 0
	v_addc_co_u32_e32 v105, vcc, 0, v121, vcc
	v_add_co_u32_e32 v112, vcc, s70, v120
	v_lshl_add_u64 v[124:125], s[22:23], 0, v[96:97]
	s_nop 0
	v_addc_co_u32_e32 v113, vcc, 0, v121, vcc
	v_add_co_u32_e32 v116, vcc, 0x8000, v120
	s_nop 0
	s_nop 0
	v_addc_co_u32_e32 v117, vcc, 0, v121, vcc
	v_add_co_u32_e32 v120, vcc, 0xd000, v120
	s_nop 0
	s_nop 0
	v_addc_co_u32_e32 v121, vcc, 0, v121, vcc
	v_add_co_u32_e32 v124, vcc, 0x2000, v124
	s_nop 0
	s_nop 0
	v_addc_co_u32_e32 v125, vcc, 0, v125, vcc
	v_mov_b32_e32 v192, 0
	v_mov_b32_e32 v198, 0
	v_mov_b32_e32 v199, 0
	v_mov_b32_e32 v200, 0
	v_mov_b32_e32 v201, 0
	v_mov_b32_e32 v206, 0
	v_mov_b32_e32 v207, 0
	v_mov_b32_e32 v208, 0
	v_mov_b32_e32 v209, 0
	v_mov_b32_e32 v194, 0
	v_mov_b32_e32 v195, 0
	v_mov_b32_e32 v196, 0
	v_mov_b32_e32 v197, 0
	v_mov_b32_e32 v202, 0
	v_mov_b32_e32 v203, 0
	v_mov_b32_e32 v204, 0
	v_mov_b32_e32 v205, 0
	s_and_saveexec_b64 s[42:43], s[26:27]
	s_cbranch_execz .LBB0_767
	ds_read_b128 v[202:205], v238
	ds_read_b128 v[206:209], v238 offset:512
	ds_read_b128 v[194:197], v238 offset:1024
	ds_read_b128 v[198:201], v238 offset:1536
.LBB0_767:
	s_or_b64 exec, exec, s[42:43]
	s_waitcnt lgkmcnt(0)
	v_mov_b32_dpp v198, v140 row_shr:1 row_mask:0xf bank_mask:0xf
	v_mov_b32_dpp v199, v141 row_shr:1 row_mask:0xf bank_mask:0xf
	s_waitcnt vmcnt(8)
	v_and_b32_e32 v253, 0xf0, v219
	v_lshlrev_b32_e32 v253, 4, v253
	v_add_u32_e32 v253, 0x22000, v253
	ds_read_b128 v[160:163], v253
	ds_read_b128 v[164:167], v253 offset:16
	ds_read_b128 v[168:171], v253 offset:32
	ds_read_b128 v[172:175], v253 offset:48
	ds_read_b128 v[176:179], v253 offset:64
	ds_read_b128 v[180:183], v253 offset:80
	ds_read_b128 v[184:187], v253 offset:96
	ds_read_b128 v[188:191], v253 offset:112
	ds_read_b128 v[96:99], v253 offset:128
	ds_read_b128 v[100:103], v253 offset:144
	ds_read_b128 v[104:107], v253 offset:160
	ds_read_b128 v[108:111], v253 offset:176
	ds_read_b128 v[112:115], v253 offset:192
	ds_read_b128 v[116:119], v253 offset:208
	ds_read_b128 v[120:123], v253 offset:224
	ds_read_b128 v[124:127], v253 offset:240
	s_waitcnt lgkmcnt(0)
	v_lshlrev_b32_e32 v253, 2, v218
	s_and_saveexec_b64 s[46:47], s[12:13]
	s_cbranch_execz .LBB0_763
	global_store_dwordx4 v253, v[156:159], s[44:45]
	global_store_dwordx4 v253, v[144:147], s[44:45] offset:1024
	global_store_dwordx4 v253, v[60:63], s[44:45] offset:16
	global_store_dwordx4 v253, v[48:51], s[44:45] offset:1040
	global_store_dwordx4 v253, v[152:155], s[44:45] offset:512
	global_store_dwordx4 v253, v[132:135], s[44:45] offset:1536
	global_store_dwordx4 v253, v[56:59], s[44:45] offset:528
	global_store_dwordx4 v253, v[36:39], s[44:45] offset:1552

; #define PG8_STAGE(bufoff, gbase, voff) do { _Pragma("unroll") for (int _i = 0; _i < 2; ++_i) \
;         __builtin_amdgcn_global_load_lds((const unsigned*)((const char*)(gbase) + (voff)[_i]), (LAS unsigned*)(lds + (bufoff) + ldsw + _i * 8192), 16, 0, 0); } while (0)
; #define PG8_LDA(dst, b, h) do { _Pragma("unroll") for (int m = 0; m < 4; ++m) _Pragma("unroll") for (int k = 0; k < 2; ++k) dst[m][k] = *(const LAS bf16x8*)(lds + PG8_SA(b, h) + aoff + m * 2048 + k * 1024); } while (0)
; #define PG8_LDB(dst, b, h) do { _Pragma("unroll") for (int n = 0; n < 2; ++n) _Pragma("unroll") for (int k = 0; k < 2; ++k) dst[n][k] = *(const LAS bf16x8*)(lds + PG8_SB(b, h) + boff + n * 2048 + k * 1024); } while (0)
; #define PG8_MMA(ai, bj, At, Bt) do { __builtin_amdgcn_s_setprio(1); _Pragma("unroll") for (int m = 0; m < 4; ++m) _Pragma("unroll") for (int n = 0; n < 2; ++n) _Pragma("unroll") for (int k = 0; k < 2; ++k) \
;         acc[ai][bj][m][n] = __builtin_amdgcn_mfma_f32_16x16x32_bf16(Bt[n][k], At[m][k], acc[ai][bj][m][n], 0, 0, 0); __builtin_amdgcn_s_setprio(0); } while (0)
; #define PG8_WAIT_L(n) asm volatile("s_waitcnt lgkmcnt(" #n ")" ::: "memory")
; #define PG8_BAR __builtin_amdgcn_s_barrier()
; #define PG8_SCHED __builtin_amdgcn_sched_barrier(0)
; template <class Epi>
; __device__ __forceinline__ void gemm_phase(LAS unsigned char* lds, const Gemm g, const StaticOrder& S, const Epi& E) {
;     ...
;             PG8_LDB(B0, 0, 0); PG8_SCHED; PG8_LDA(At, 0, 0); PG8_STAGE(PG8_SA(1, 1), a1 + hstepA, voffA);
;             PG8_WAIT_L(8); PG8_BAR; PG8_WAIT_L(0); PG8_MMA(0, 0, At, B0); PG8_BAR; PG8_SCHED;
;             PG8_LDB(B1, 0, 1); PG8_STAGE(PG8_SB(0, 0), b2, voffB);
;             PG8_BAR; PG8_WAIT_L(0); PG8_MMA(0, 1, At, B1); PG8_BAR;
;             PG8_LDA(At, 0, 1); PG8_STAGE(PG8_SA(0, 0), a2, voffA);
;             PG8_BAR; PG8_WAIT_L(0); PG8_MMA(1, 0, At, B0); PG8_BAR; PG8_SCHED;
.LBB0_1359:
	ds_read_b128 v[96:99], v243
	ds_read_b128 v[100:103], v243 offset:1024
	ds_read_b128 v[104:107], v243 offset:2048
	ds_read_b128 v[108:111], v243 offset:3072
	s_add_u32 s46, s44, 0x100
	s_addc_u32 s47, s45, 0
	s_cmp_eq_u32 s87, 12
	s_cselect_b32 s73, s37, s47
	s_cselect_b32 s72, s83, s46
	s_cselect_b32 s49, s35, s86
	s_cselect_b32 s48, s84, s85
	v_lshl_add_u64 v[176:177], s[44:45], 0, v[224:225]
	s_add_i32 m0, s9, 0xc000
	ds_read_b128 v[112:115], v244
	ds_read_b128 v[116:119], v244 offset:1024
	ds_read_b128 v[120:123], v244 offset:2048
	ds_read_b128 v[124:127], v244 offset:3072
	ds_read_b128 v[160:163], v244 offset:4096
	ds_read_b128 v[164:167], v244 offset:5120
	ds_read_b128 v[168:171], v244 offset:6144
	ds_read_b128 v[172:175], v244 offset:7168
	global_load_lds_dwordx4 v[176:177], off
	v_lshl_add_u64 v[176:177], s[44:45], 0, v[226:227]
	s_add_i32 m0, s9, 0xe000
	s_nop 0
	global_load_lds_dwordx4 v[176:177], off
	ds_read_b128 v[176:179], v245
	ds_read_b128 v[180:183], v245 offset:1024
	ds_read_b128 v[184:187], v245 offset:2048
	ds_read_b128 v[188:191], v245 offset:3072
	s_waitcnt lgkmcnt(0)
	s_barrier
	s_setprio 1
	v_mfma_f32_16x16x32_bf16 v[156:159], v[96:99], v[112:115], v[156:159]
	v_mfma_f32_16x16x32_bf16 v[60:63], v[104:107], v[112:115], v[60:63]
	v_mfma_f32_16x16x32_bf16 v[144:147], v[96:99], v[120:123], v[144:147]
	v_mfma_f32_16x16x32_bf16 v[48:51], v[104:107], v[120:123], v[48:51]
	v_mfma_f32_16x16x32_bf16 v[136:139], v[96:99], v[160:163], v[136:139]
	v_mfma_f32_16x16x32_bf16 v[40:43], v[104:107], v[160:163], v[40:43]
	v_mfma_f32_16x16x32_bf16 v[148:151], v[96:99], v[168:171], v[148:151]
	v_mfma_f32_16x16x32_bf16 v[52:55], v[104:107], v[168:171], v[52:55]
	v_mfma_f32_16x16x32_bf16 v[156:159], v[100:103], v[116:119], v[156:159]
	v_mfma_f32_16x16x32_bf16 v[60:63], v[108:111], v[116:119], v[60:63]
	v_mfma_f32_16x16x32_bf16 v[144:147], v[100:103], v[124:127], v[144:147]
	v_mfma_f32_16x16x32_bf16 v[48:51], v[108:111], v[124:127], v[48:51]
	v_mfma_f32_16x16x32_bf16 v[136:139], v[100:103], v[164:167], v[136:139]
	v_mfma_f32_16x16x32_bf16 v[40:43], v[108:111], v[164:167], v[40:43]
	v_mfma_f32_16x16x32_bf16 v[148:151], v[100:103], v[172:175], v[148:151]
	v_mfma_f32_16x16x32_bf16 v[52:55], v[108:111], v[172:175], v[52:55]
	v_mfma_f32_16x16x32_bf16 v[152:155], v[176:179], v[112:115], v[152:155]
	v_mfma_f32_16x16x32_bf16 v[56:59], v[184:187], v[112:115], v[56:59]
	v_mfma_f32_16x16x32_bf16 v[36:39], v[184:187], v[120:123], v[36:39]
	v_mfma_f32_16x16x32_bf16 v[32:35], v[184:187], v[160:163], v[32:35]
	v_mfma_f32_16x16x32_bf16 v[44:47], v[184:187], v[168:171], v[44:47]
	v_mfma_f32_16x16x32_bf16 v[152:155], v[180:183], v[116:119], v[152:155]
	v_mfma_f32_16x16x32_bf16 v[56:59], v[188:191], v[116:119], v[56:59]
	v_mfma_f32_16x16x32_bf16 v[112:115], v[176:179], v[120:123], v[132:135]
	v_mfma_f32_16x16x32_bf16 v[36:39], v[188:191], v[124:127], v[36:39]
	v_mfma_f32_16x16x32_bf16 v[116:119], v[176:179], v[160:163], v[128:131]
	v_mfma_f32_16x16x32_bf16 v[32:35], v[188:191], v[164:167], v[32:35]
	v_mfma_f32_16x16x32_bf16 v[120:123], v[176:179], v[168:171], v[140:143]
	v_mfma_f32_16x16x32_bf16 v[44:47], v[188:191], v[172:175], v[44:47]
	v_mfma_f32_16x16x32_bf16 v[112:115], v[180:183], v[124:127], v[112:115]
	v_mfma_f32_16x16x32_bf16 v[116:119], v[180:183], v[164:167], v[116:119]
	v_mfma_f32_16x16x32_bf16 v[120:123], v[180:183], v[172:175], v[120:123]
	s_setprio 0
	s_barrier
	s_nop 1
	ds_read_b128 v[124:127], v244 offset:16384
	ds_read_b128 v[128:131], v244 offset:17408
	ds_read_b128 v[132:135], v244 offset:18432
	ds_read_b128 v[140:143], v244 offset:19456
	ds_read_b128 v[160:163], v244 offset:20480
	ds_read_b128 v[164:167], v244 offset:21504
	ds_read_b128 v[168:171], v244 offset:22528
	ds_read_b128 v[172:175], v244 offset:23552
	s_add_i32 s44, s80, s7
	v_lshl_add_u64 v[196:197], s[48:49], 0, v[214:215]
	s_mov_b32 m0, s44
	s_nop 0
	global_load_lds_dwordx4 v[196:197], off
	v_lshl_add_u64 v[198:199], s[48:49], 0, v[210:211]
	s_add_i32 m0, s44, 0x2000
	s_nop 0
	global_load_lds_dwordx4 v[198:199], off
	s_mov_b32 m0, s9
	v_lshl_add_u64 v[200:201], s[72:73], 0, v[216:217]
	global_load_lds_dwordx4 v[200:201], off
	v_lshl_add_u64 v[202:203], s[72:73], 0, v[212:213]
	s_mov_b32 m0, s63
	s_nop 0
	global_load_lds_dwordx4 v[202:203], off
	s_add_u32 s44, s48, 0x40000
	s_addc_u32 s45, s49, 0
	s_add_i32 s88, s81, s7
	v_lshl_add_u64 v[254:255], s[44:45], 0, v[214:215]
	s_mov_b32 m0, s88
	s_nop 0
	global_load_lds_dwordx4 v[254:255], off
	v_lshl_add_u64 v[254:255], s[44:45], 0, v[210:211]
	s_add_i32 m0, s88, 0x2000
	s_nop 0
	global_load_lds_dwordx4 v[254:255], off
	s_waitcnt vmcnt(6)
	s_waitcnt lgkmcnt(0)
	s_barrier
; #define PG8_STAGE(bufoff, gbase, voff) do { _Pragma("unroll") for (int _i = 0; _i < 2; ++_i) \
;         __builtin_amdgcn_global_load_lds((const unsigned*)((const char*)(gbase) + (voff)[_i]), (LAS unsigned*)(lds + (bufoff) + ldsw + _i * 8192), 16, 0, 0); } while (0)
; #define PG8_LDA(dst, b, h) do { _Pragma("unroll") for (int m = 0; m < 4; ++m) _Pragma("unroll") for (int k = 0; k < 2; ++k) dst[m][k] = *(const LAS bf16x8*)(lds + PG8_SA(b, h) + aoff + m * 2048 + k * 1024); } while (0)
; #define PG8_LDB(dst, b, h) do { _Pragma("unroll") for (int n = 0; n < 2; ++n) _Pragma("unroll") for (int k = 0; k < 2; ++k) dst[n][k] = *(const LAS bf16x8*)(lds + PG8_SB(b, h) + boff + n * 2048 + k * 1024); } while (0)
; #define PG8_MMA(ai, bj, At, Bt) do { __builtin_amdgcn_s_setprio(1); _Pragma("unroll") for (int m = 0; m < 4; ++m) _Pragma("unroll") for (int n = 0; n < 2; ++n) _Pragma("unroll") for (int k = 0; k < 2; ++k) \
;         acc[ai][bj][m][n] = __builtin_amdgcn_mfma_f32_16x16x32_bf16(Bt[n][k], At[m][k], acc[ai][bj][m][n], 0, 0, 0); __builtin_amdgcn_s_setprio(0); } while (0)
; #define PG8_WAIT_V(n) asm volatile("s_waitcnt vmcnt(" #n ")" ::: "memory")
; #define PG8_WAIT_L(n) asm volatile("s_waitcnt lgkmcnt(" #n ")" ::: "memory")
; #define PG8_BAR __builtin_amdgcn_s_barrier()
; #define PG8_SCHED __builtin_amdgcn_sched_barrier(0)
; template <class Epi>
; __device__ __forceinline__ void gemm_phase(LAS unsigned char* lds, const Gemm g, const StaticOrder& S, const Epi& E) {
;     ...
;             PG8_BAR; PG8_WAIT_L(0); PG8_MMA(1, 0, At, B0); PG8_BAR; PG8_SCHED;
;             PG8_STAGE(PG8_SB(0, 1), b2 + hstepB, voffB);
;             PG8_WAIT_V(6); PG8_BAR; PG8_MMA(1, 1, At, B1); PG8_BAR;
;             PG8_LDB(B0, 1, 0); PG8_SCHED; PG8_LDA(At, 1, 0); PG8_STAGE(PG8_SA(0, 1), a2 + hstepA, voffA);
;             PG8_WAIT_L(8); PG8_BAR; PG8_WAIT_L(0); PG8_MMA(0, 0, At, B0); PG8_BAR; PG8_SCHED;
;             PG8_LDB(B1, 1, 1); PG8_STAGE(PG8_SB(1, 0), b3, voffB);
;             PG8_BAR; PG8_WAIT_L(0); PG8_MMA(0, 1, At, B1); PG8_BAR;
	s_setprio 1
	v_mfma_f32_16x16x32_bf16 v[92:95], v[96:99], v[124:127], v[92:95]
	v_mfma_f32_16x16x32_bf16 v[28:31], v[104:107], v[124:127], v[28:31]
	v_mfma_f32_16x16x32_bf16 v[80:83], v[96:99], v[132:135], v[80:83]
	v_mfma_f32_16x16x32_bf16 v[16:19], v[104:107], v[132:135], v[16:19]
	v_mfma_f32_16x16x32_bf16 v[76:79], v[96:99], v[160:163], v[76:79]
	v_mfma_f32_16x16x32_bf16 v[12:15], v[104:107], v[160:163], v[12:15]
	v_mfma_f32_16x16x32_bf16 v[84:87], v[96:99], v[168:171], v[84:87]
	v_mfma_f32_16x16x32_bf16 v[20:23], v[104:107], v[168:171], v[20:23]
	v_mfma_f32_16x16x32_bf16 v[92:95], v[100:103], v[128:131], v[92:95]
	v_mfma_f32_16x16x32_bf16 v[28:31], v[108:111], v[128:131], v[28:31]
	v_mfma_f32_16x16x32_bf16 v[80:83], v[100:103], v[140:143], v[80:83]
	v_mfma_f32_16x16x32_bf16 v[16:19], v[108:111], v[140:143], v[16:19]
	v_mfma_f32_16x16x32_bf16 v[76:79], v[100:103], v[164:167], v[76:79]
	v_mfma_f32_16x16x32_bf16 v[12:15], v[108:111], v[164:167], v[12:15]
	v_mfma_f32_16x16x32_bf16 v[84:87], v[100:103], v[172:175], v[84:87]
	v_mfma_f32_16x16x32_bf16 v[20:23], v[108:111], v[172:175], v[20:23]
	v_mfma_f32_16x16x32_bf16 v[88:91], v[176:179], v[124:127], v[88:91]
	v_mfma_f32_16x16x32_bf16 v[24:27], v[184:187], v[124:127], v[24:27]
	v_mfma_f32_16x16x32_bf16 v[68:71], v[176:179], v[132:135], v[68:71]
	v_mfma_f32_16x16x32_bf16 v[4:7], v[184:187], v[132:135], v[4:7]
	v_mfma_f32_16x16x32_bf16 v[64:67], v[176:179], v[160:163], v[64:67]
	v_mfma_f32_16x16x32_bf16 v[0:3], v[184:187], v[160:163], v[0:3]
	v_mfma_f32_16x16x32_bf16 v[72:75], v[176:179], v[168:171], v[72:75]
	v_mfma_f32_16x16x32_bf16 v[8:11], v[184:187], v[168:171], v[8:11]
	v_mfma_f32_16x16x32_bf16 v[88:91], v[180:183], v[128:131], v[88:91]
	v_mfma_f32_16x16x32_bf16 v[24:27], v[188:191], v[128:131], v[24:27]
	v_mfma_f32_16x16x32_bf16 v[68:71], v[180:183], v[140:143], v[68:71]
	v_mfma_f32_16x16x32_bf16 v[4:7], v[188:191], v[140:143], v[4:7]
	v_mfma_f32_16x16x32_bf16 v[64:67], v[180:183], v[164:167], v[64:67]
	v_mfma_f32_16x16x32_bf16 v[0:3], v[188:191], v[164:167], v[0:3]
	v_mfma_f32_16x16x32_bf16 v[72:75], v[180:183], v[172:175], v[72:75]
	v_mfma_f32_16x16x32_bf16 v[8:11], v[188:191], v[172:175], v[8:11]
	s_setprio 0
	s_add_i32 s88, 0, 0x18000
	v_add_u32_e32 v108, s88, v235
	s_barrier
	ds_read_b128 v[96:99], v108
	ds_read_b128 v[100:103], v108 offset:1024
	ds_read_b128 v[104:107], v108 offset:2048
	ds_read_b128 v[108:111], v108 offset:3072
	s_add_u32 s44, s72, 0x40000
	s_addc_u32 s45, s73, 0
	s_mov_b32 m0, s74
	v_lshl_add_u64 v[132:133], s[44:45], 0, v[216:217]
	ds_read_b128 v[124:127], v244 offset:32768
	ds_read_b128 v[128:131], v244 offset:33792
	ds_read_b128 v[140:143], v244 offset:34816
	ds_read_b128 v[160:163], v244 offset:35840
	ds_read_b128 v[164:167], v244 offset:36864
	ds_read_b128 v[168:171], v244 offset:37888
	ds_read_b128 v[172:175], v244 offset:38912
	ds_read_b128 v[176:179], v244 offset:39936
	global_load_lds_dwordx4 v[132:133], off
	v_lshl_add_u64 v[132:133], s[44:45], 0, v[212:213]
	s_mov_b32 m0, s75
	s_nop 0
	global_load_lds_dwordx4 v[132:133], off
	s_add_i32 s72, 0, 0x1c000
	v_add_u32_e32 v132, s72, v235
	ds_read_b128 v[180:183], v132
	ds_read_b128 v[184:187], v132 offset:1024
	ds_read_b128 v[188:191], v132 offset:2048
	ds_read_b128 v[192:195], v132 offset:3072
	s_waitcnt lgkmcnt(0)
	s_barrier
	s_setprio 1
	v_mfma_f32_16x16x32_bf16 v[132:135], v[96:99], v[124:127], v[156:159]
	v_mfma_f32_16x16x32_bf16 v[156:159], v[100:103], v[128:131], v[132:135]
	v_mfma_f32_16x16x32_bf16 v[132:135], v[96:99], v[140:143], v[144:147]
	v_mfma_f32_16x16x32_bf16 v[144:147], v[100:103], v[160:163], v[132:135]
	v_mfma_f32_16x16x32_bf16 v[132:135], v[96:99], v[164:167], v[136:139]
	v_mfma_f32_16x16x32_bf16 v[60:63], v[104:107], v[124:127], v[60:63]
	v_mfma_f32_16x16x32_bf16 v[48:51], v[104:107], v[140:143], v[48:51]
	v_mfma_f32_16x16x32_bf16 v[136:139], v[100:103], v[168:171], v[132:135]
	v_mfma_f32_16x16x32_bf16 v[40:43], v[104:107], v[164:167], v[40:43]
	v_mfma_f32_16x16x32_bf16 v[132:135], v[96:99], v[172:175], v[148:151]
	v_mfma_f32_16x16x32_bf16 v[52:55], v[104:107], v[172:175], v[52:55]
	v_mfma_f32_16x16x32_bf16 v[60:63], v[108:111], v[128:131], v[60:63]
	v_mfma_f32_16x16x32_bf16 v[48:51], v[108:111], v[160:163], v[48:51]
	v_mfma_f32_16x16x32_bf16 v[40:43], v[108:111], v[168:171], v[40:43]
	v_mfma_f32_16x16x32_bf16 v[148:151], v[100:103], v[176:179], v[132:135]
	v_mfma_f32_16x16x32_bf16 v[52:55], v[108:111], v[176:179], v[52:55]
	v_mfma_f32_16x16x32_bf16 v[132:135], v[180:183], v[124:127], v[152:155]
	v_mfma_f32_16x16x32_bf16 v[112:115], v[180:183], v[140:143], v[112:115]
	v_mfma_f32_16x16x32_bf16 v[152:155], v[184:187], v[128:131], v[132:135]
	v_mfma_f32_16x16x32_bf16 v[56:59], v[188:191], v[124:127], v[56:59]
	v_mfma_f32_16x16x32_bf16 v[132:135], v[184:187], v[160:163], v[112:115]
	v_mfma_f32_16x16x32_bf16 v[112:115], v[180:183], v[164:167], v[116:119]
	v_mfma_f32_16x16x32_bf16 v[56:59], v[192:195], v[128:131], v[56:59]
	v_mfma_f32_16x16x32_bf16 v[36:39], v[188:191], v[140:143], v[36:39]
	v_mfma_f32_16x16x32_bf16 v[128:131], v[184:187], v[168:171], v[112:115]
	v_mfma_f32_16x16x32_bf16 v[32:35], v[188:191], v[164:167], v[32:35]
	v_mfma_f32_16x16x32_bf16 v[112:115], v[180:183], v[172:175], v[120:123]
	v_mfma_f32_16x16x32_bf16 v[44:47], v[188:191], v[172:175], v[44:47]
	v_mfma_f32_16x16x32_bf16 v[36:39], v[192:195], v[160:163], v[36:39]
	v_mfma_f32_16x16x32_bf16 v[32:35], v[192:195], v[168:171], v[32:35]
	v_mfma_f32_16x16x32_bf16 v[140:143], v[184:187], v[176:179], v[112:115]
	v_mfma_f32_16x16x32_bf16 v[44:47], v[192:195], v[176:179], v[44:47]
	s_setprio 0
	s_barrier
; #define PG8_STAGE(bufoff, gbase, voff) do { _Pragma("unroll") for (int _i = 0; _i < 2; ++_i) \
;         __builtin_amdgcn_global_load_lds((const unsigned*)((const char*)(gbase) + (voff)[_i]), (LAS unsigned*)(lds + (bufoff) + ldsw + _i * 8192), 16, 0, 0); } while (0)
; #define PG8_LDA(dst, b, h) do { _Pragma("unroll") for (int m = 0; m < 4; ++m) _Pragma("unroll") for (int k = 0; k < 2; ++k) dst[m][k] = *(const LAS bf16x8*)(lds + PG8_SA(b, h) + aoff + m * 2048 + k * 1024); } while (0)
; #define PG8_MMA(ai, bj, At, Bt) do { __builtin_amdgcn_s_setprio(1); _Pragma("unroll") for (int m = 0; m < 4; ++m) _Pragma("unroll") for (int n = 0; n < 2; ++n) _Pragma("unroll") for (int k = 0; k < 2; ++k) \
;         acc[ai][bj][m][n] = __builtin_amdgcn_mfma_f32_16x16x32_bf16(Bt[n][k], At[m][k], acc[ai][bj][m][n], 0, 0, 0); __builtin_amdgcn_s_setprio(0); } while (0)
; #define PG8_WAIT_V(n) asm volatile("s_waitcnt vmcnt(" #n ")" ::: "memory")
; #define PG8_WAIT_L(n) asm volatile("s_waitcnt lgkmcnt(" #n ")" ::: "memory")
; #define PG8_BAR __builtin_amdgcn_s_barrier()
; #define PG8_SCHED __builtin_amdgcn_sched_barrier(0)
; template <class Epi>
; __device__ __forceinline__ void gemm_phase(LAS unsigned char* lds, const Gemm g, const StaticOrder& S, const Epi& E) {
;     ...
;             PG8_LDA(At, 1, 1); PG8_STAGE(PG8_SA(1, 0), a3, voffA);
;             PG8_BAR; PG8_WAIT_L(0); PG8_MMA(1, 0, At, B0); PG8_BAR; PG8_SCHED;
;             PG8_STAGE(PG8_SB(1, 1), b3 + hstepB, voffB);
;             PG8_WAIT_V(6); PG8_BAR; PG8_MMA(1, 1, At, B1); PG8_BAR;
;     __device__ __forceinline__ void operator()(AccRef acc, const Unit& u, int wr, int wc, int fr, int fq) const {
;     ...
;         { const float* cv = cw + 128 * u.pn + clb; const float* cg = cv + FH; const float* bp = cb + 128 * u.pn + clb;
;           cwv[0][0] = *(const f32x4*)(cv); cwv[0][1] = *(const f32x4*)(cv + F2); cwv[0][2] = *(const f32x4*)(cv + 2 * F2); cwv[0][3] = *(const f32x4*)(bp);
;           cwv[0][4] = *(const f32x4*)(cg); cwv[0][5] = *(const f32x4*)(cg + F2); cwv[0][6] = *(const f32x4*)(cg + 2 * F2); cwv[0][7] = *(const f32x4*)(bp + FH); }
	s_nop 1
	ds_read_b128 v[112:115], v244 offset:49152
	ds_read_b128 v[116:119], v244 offset:50176
	ds_read_b128 v[120:123], v244 offset:51200
	ds_read_b128 v[124:127], v244 offset:52224
	ds_read_b128 v[160:163], v244 offset:53248
	ds_read_b128 v[164:167], v244 offset:54272
	ds_read_b128 v[168:171], v244 offset:55296
	ds_read_b128 v[172:175], v244 offset:56320
	s_add_i32 s44, s88, s7
	v_lshl_add_u64 v[254:255], v[196:197], 0, s[24:25]
	s_mov_b32 m0, s44
	s_nop 0
	global_load_lds_dwordx4 v[254:255], off
	v_lshl_add_u64 v[254:255], v[198:199], 0, s[24:25]
	s_add_i32 m0, s44, 0x2000
	s_nop 0
	global_load_lds_dwordx4 v[254:255], off
	s_mov_b32 m0, s78
	v_lshl_add_u64 v[254:255], v[200:201], 0, s[24:25]
	global_load_lds_dwordx4 v[254:255], off
	v_lshl_add_u64 v[254:255], v[202:203], 0, s[24:25]
	s_mov_b32 m0, s79
	s_nop 0
	global_load_lds_dwordx4 v[254:255], off
	s_add_u32 s44, s48, 0x40080
	s_addc_u32 s45, s49, 0
	s_add_i32 s48, s72, s7
	v_lshl_add_u64 v[254:255], s[44:45], 0, v[214:215]
	s_mov_b32 m0, s48
	s_nop 0
	global_load_lds_dwordx4 v[254:255], off
	v_lshl_add_u64 v[254:255], s[44:45], 0, v[210:211]
	s_add_i32 m0, s48, 0x2000
	s_nop 0
	global_load_lds_dwordx4 v[254:255], off
	s_waitcnt vmcnt(6)
	s_waitcnt lgkmcnt(0)
	s_barrier
	s_setprio 1
	v_mfma_f32_16x16x32_bf16 v[92:95], v[96:99], v[112:115], v[92:95]
	v_mfma_f32_16x16x32_bf16 v[28:31], v[104:107], v[112:115], v[28:31]
	v_mfma_f32_16x16x32_bf16 v[80:83], v[96:99], v[120:123], v[80:83]
	v_mfma_f32_16x16x32_bf16 v[16:19], v[104:107], v[120:123], v[16:19]
	v_mfma_f32_16x16x32_bf16 v[76:79], v[96:99], v[160:163], v[76:79]
	v_mfma_f32_16x16x32_bf16 v[12:15], v[104:107], v[160:163], v[12:15]
	v_mfma_f32_16x16x32_bf16 v[84:87], v[96:99], v[168:171], v[84:87]
	v_mfma_f32_16x16x32_bf16 v[20:23], v[104:107], v[168:171], v[20:23]
	v_mfma_f32_16x16x32_bf16 v[92:95], v[100:103], v[116:119], v[92:95]
	v_mfma_f32_16x16x32_bf16 v[28:31], v[108:111], v[116:119], v[28:31]
	v_mfma_f32_16x16x32_bf16 v[80:83], v[100:103], v[124:127], v[80:83]
	v_mfma_f32_16x16x32_bf16 v[16:19], v[108:111], v[124:127], v[16:19]
	v_mfma_f32_16x16x32_bf16 v[76:79], v[100:103], v[164:167], v[76:79]
	v_mfma_f32_16x16x32_bf16 v[12:15], v[108:111], v[164:167], v[12:15]
	v_mfma_f32_16x16x32_bf16 v[84:87], v[100:103], v[172:175], v[84:87]
	v_mfma_f32_16x16x32_bf16 v[20:23], v[108:111], v[172:175], v[20:23]
	v_mfma_f32_16x16x32_bf16 v[88:91], v[180:183], v[112:115], v[88:91]
	v_mfma_f32_16x16x32_bf16 v[24:27], v[188:191], v[112:115], v[24:27]
	v_mfma_f32_16x16x32_bf16 v[68:71], v[180:183], v[120:123], v[68:71]
	v_mfma_f32_16x16x32_bf16 v[4:7], v[188:191], v[120:123], v[4:7]
	v_mfma_f32_16x16x32_bf16 v[64:67], v[180:183], v[160:163], v[64:67]
	v_mfma_f32_16x16x32_bf16 v[0:3], v[188:191], v[160:163], v[0:3]
	v_mfma_f32_16x16x32_bf16 v[72:75], v[180:183], v[168:171], v[72:75]
	v_mfma_f32_16x16x32_bf16 v[8:11], v[188:191], v[168:171], v[8:11]
	v_mfma_f32_16x16x32_bf16 v[88:91], v[184:187], v[116:119], v[88:91]
	v_mfma_f32_16x16x32_bf16 v[24:27], v[192:195], v[116:119], v[24:27]
	v_mfma_f32_16x16x32_bf16 v[68:71], v[184:187], v[124:127], v[68:71]
	v_mfma_f32_16x16x32_bf16 v[4:7], v[192:195], v[124:127], v[4:7]
	v_mfma_f32_16x16x32_bf16 v[64:67], v[184:187], v[164:167], v[64:67]
	v_mfma_f32_16x16x32_bf16 v[0:3], v[192:195], v[164:167], v[0:3]
	v_mfma_f32_16x16x32_bf16 v[72:75], v[184:187], v[172:175], v[72:75]
	v_mfma_f32_16x16x32_bf16 v[8:11], v[192:195], v[172:175], v[8:11]
	s_setprio 0
	s_add_i32 s87, s87, 2
	s_add_u32 s85, s85, 0x100
	s_addc_u32 s86, s86, 0
	s_cmp_gt_u32 s87, 13
	s_mov_b64 s[44:45], s[46:47]
	s_barrier
	s_cbranch_scc0 .LBB0_1359
	s_lshl_b32 s44, s43, 7
	s_ashr_i32 s45, s44, 31
	s_lshl_b64 s[46:47], s[44:45], 2
	v_readfirstlane_b32 s99, v219
	v_and_b32_e32 v96, 15, v219
	v_and_b32_e32 v97, 3, v96
	v_mul_u32_u24_e32 v98, 0x5800, v97
	v_cmp_eq_u32_e32 vcc, 3, v97
	v_bfe_u32 v99, v96, 2, 1
	v_mul_u32_u24_e32 v99, 0x2c00, v99
	v_cndmask_b32_e64 v98, v98, 0, vcc
	v_add_u32_e32 v98, v98, v99
	v_bfe_u32 v99, v96, 3, 1
	v_lshl_add_u32 v98, v99, 4, v98
	v_add_u32_e32 v98, s46, v98
	v_cndmask_b32_e32 v100, v220, v222, vcc
	v_cndmask_b32_e32 v101, v221, v223, vcc
	v_add_co_u32_e32 v100, vcc, v100, v98
	s_nop 1
	v_addc_co_u32_e32 v101, vcc, 0, v101, vcc
	s_bitcmp1_b32 s99, 8
	s_cbranch_scc1 .Lcw1359_skip
	global_load_dwordx4 v[108:111], v[100:101], off
;     __device__ __forceinline__ void operator()(AccRef acc, const Unit& u, int wr, int wc, int fr, int fq) const {
;         const int clb = 32 * wc + 8 * fq;
;         f32x4 cwv[2][8];
;         { const float* cv = cw + 128 * u.pn + clb; const float* cg = cv + FH; const float* bp = cb + 128 * u.pn + clb;
;           cwv[0][0] = *(const f32x4*)(cv); cwv[0][1] = *(const f32x4*)(cv + F2); cwv[0][2] = *(const f32x4*)(cv + 2 * F2); cwv[0][3] = *(const f32x4*)(bp);
;           cwv[0][4] = *(const f32x4*)(cg); cwv[0][5] = *(const f32x4*)(cg + F2); cwv[0][6] = *(const f32x4*)(cg + 2 * F2); cwv[0][7] = *(const f32x4*)(bp + FH); }
;         if (fr == 15) {
; #pragma unroll
;             for (int ai = 0; ai < 2; ++ai)
; #pragma unroll
;                 for (int bj = 0; bj < 2; ++bj)
; #pragma unroll
;                     for (int n = 0; n < 2; ++n) { *(LAS f32x4*)(xch + ((ai * 2 + wr) * 2 + 0) * 256 + bj * 128 + clb + 4 * n) = acc[ai][bj][2][n]; *(LAS f32x4*)(xch + ((ai * 2 + wr) * 2 + 1) * 256 + bj * 128 + clb + 4 * n) = acc[ai][bj][3][n]; }
;         }
;         float* rawu = raw + (size_t)(u.pm * 22 + u.pn) * 1024;
;         if (wr == 0 && fr == 0) {
; #pragma unroll
;             for (int bj = 0; bj < 2; ++bj)
; #pragma unroll
;                 for (int n = 0; n < 2; ++n) { *(f32x4*)(rawu + 0 * 256 + bj * 128 + clb + 4 * n) = acc[0][bj][0][n]; *(f32x4*)(rawu + 1 * 256 + bj * 128 + clb + 4 * n) = acc[0][bj][1][n]; }
;         }
;         if (wr == 1 && fr == 15) {
; #pragma unroll
;             for (int bj = 0; bj < 2; ++bj)
; #pragma unroll
;                 for (int n = 0; n < 2; ++n) { *(f32x4*)(rawu + 2 * 256 + bj * 128 + clb + 4 * n) = acc[1][bj][2][n]; *(f32x4*)(rawu + 3 * 256 + bj * 128 + clb + 4 * n) = acc[1][bj][3][n]; }
;         }
;         asm volatile("s_waitcnt lgkmcnt(0)" ::: "memory"); __builtin_amdgcn_s_barrier(); __builtin_amdgcn_s_barrier(); asm volatile("" ::: "memory");
;         const int hc0 = 128 * u.pn + clb, row0 = u.pm * 256 + wr * 64 + 4 * fr;
; #pragma unroll
;         for (int n = 0; n < 2; ++n) {
;             const f32x4 w0v = cwv[n][0], w1v = cwv[n][1], w2v = cwv[n][2], bvv = cwv[n][3], w0g = cwv[n][4], w1g = cwv[n][5], w2g = cwv[n][6], bvg = cwv[n][7];
; #pragma unroll
;             for (int ai = 0; ai < 2; ++ai) {
;                 if (n == 0 && ai == 0) {
;                     asm volatile("" ::: "memory");
.Lcw1359_skip:
	s_and_saveexec_b64 s[46:47], s[10:11]
	s_cbranch_execz .LBB0_1362
	ds_write_b128 v237, v[136:139]
	ds_write_b128 v237, v[148:151] offset:1024
	ds_write_b128 v237, v[40:43] offset:16
	ds_write_b128 v237, v[52:55] offset:1040
	ds_write_b128 v237, v[128:131] offset:512
	ds_write_b128 v237, v[140:143] offset:1536
	ds_write_b128 v237, v[32:35] offset:528
	ds_write_b128 v237, v[44:47] offset:1552
	ds_write_b128 v237, v[76:79] offset:4096
	ds_write_b128 v237, v[84:87] offset:5120
	ds_write_b128 v237, v[12:15] offset:4112
	ds_write_b128 v237, v[20:23] offset:5136
	ds_write_b128 v237, v[64:67] offset:4608
	ds_write_b128 v237, v[72:75] offset:5632
	ds_write_b128 v237, v[0:3] offset:4624
	ds_write_b128 v237, v[8:11] offset:5648
.LBB0_1362:
	s_or_b64 exec, exec, s[46:47]
	s_mul_i32 s35, s42, 22
	s_add_i32 s46, s35, s43
	s_ashr_i32 s47, s46, 31
	s_lshl_b64 s[46:47], s[46:47], 12
	s_add_u32 s46, s64, s46
	s_addc_u32 s47, s65, s47
	v_lshlrev_b32_e32 v96, 2, v218
	v_or_b32_e32 v232, s44, v218
	v_ashrrev_i32_e32 v233, 31, v232
	v_lshlrev_b64 v[96:97], 2, v[232:233]
	v_lshl_add_u64 v[120:121], s[16:17], 0, v[96:97]
	v_add_co_u32_e32 v100, vcc, 0x5000, v120
	s_bitcmp1_b32 s99, 8
	s_cbranch_scc1 .Lcw1359_nostage
	s_waitcnt vmcnt(0)
	v_and_b32_e32 v107, 0xff, v219
	v_lshlrev_b32_e32 v107, 4, v107
	v_add_u32_e32 v107, 0x22000, v107
	ds_write_b128 v107, v[108:111]
.Lcw1359_nostage:
	s_waitcnt lgkmcnt(0)
	s_barrier
	s_nop 0
	v_addc_co_u32_e32 v101, vcc, 0, v121, vcc
	v_add_co_u32_e32 v104, vcc, 0xb000, v120
	s_barrier
	s_nop 0
	v_addc_co_u32_e32 v105, vcc, 0, v121, vcc
	v_add_co_u32_e32 v112, vcc, s76, v120
	v_lshl_add_u64 v[124:125], s[22:23], 0, v[96:97]
	s_nop 0
	v_addc_co_u32_e32 v113, vcc, 0, v121, vcc
	v_add_co_u32_e32 v116, vcc, 0x8000, v120
	s_nop 0
	s_nop 0
	v_addc_co_u32_e32 v117, vcc, 0, v121, vcc
	v_add_co_u32_e32 v120, vcc, 0xd000, v120
	s_nop 0
	s_nop 0
	v_addc_co_u32_e32 v121, vcc, 0, v121, vcc
	v_add_co_u32_e32 v124, vcc, 0x2000, v124
	s_nop 0
	s_nop 0
	v_addc_co_u32_e32 v125, vcc, 0, v125, vcc
	v_mov_b32_e32 v192, 0
	v_mov_b32_e32 v198, 0
	v_mov_b32_e32 v199, 0
	v_mov_b32_e32 v200, 0
	v_mov_b32_e32 v201, 0
	v_mov_b32_e32 v206, 0
	v_mov_b32_e32 v207, 0
	v_mov_b32_e32 v208, 0
	v_mov_b32_e32 v209, 0
	v_mov_b32_e32 v194, 0
	v_mov_b32_e32 v195, 0
	v_mov_b32_e32 v196, 0
	v_mov_b32_e32 v197, 0
	v_mov_b32_e32 v202, 0
	v_mov_b32_e32 v203, 0
	v_mov_b32_e32 v204, 0
	v_mov_b32_e32 v205, 0
	s_and_saveexec_b64 s[44:45], s[28:29]
	s_cbranch_execz .LBB0_1368
	ds_read_b128 v[202:205], v238
	ds_read_b128 v[206:209], v238 offset:512
	ds_read_b128 v[194:197], v238 offset:1024
	ds_read_b128 v[198:201], v238 offset:1536
.LBB0_1368:
	s_or_b64 exec, exec, s[44:45]
	s_waitcnt lgkmcnt(0)
	v_mov_b32_dpp v198, v140 row_shr:1 row_mask:0xf bank_mask:0xf
	v_mov_b32_dpp v199, v141 row_shr:1 row_mask:0xf bank_mask:0xf
	s_waitcnt vmcnt(8)
	v_and_b32_e32 v253, 0xf0, v219
	v_lshlrev_b32_e32 v253, 4, v253
	v_add_u32_e32 v253, 0x22000, v253
	ds_read_b128 v[160:163], v253
	ds_read_b128 v[164:167], v253 offset:16
	ds_read_b128 v[168:171], v253 offset:32
	ds_read_b128 v[172:175], v253 offset:48
	ds_read_b128 v[176:179], v253 offset:64
	ds_read_b128 v[180:183], v253 offset:80
	ds_read_b128 v[184:187], v253 offset:96
	ds_read_b128 v[188:191], v253 offset:112
	ds_read_b128 v[96:99], v253 offset:128
	ds_read_b128 v[100:103], v253 offset:144
	ds_read_b128 v[104:107], v253 offset:160
	ds_read_b128 v[108:111], v253 offset:176
	ds_read_b128 v[112:115], v253 offset:192
	ds_read_b128 v[116:119], v253 offset:208
	ds_read_b128 v[120:123], v253 offset:224
	ds_read_b128 v[124:127], v253 offset:240
	s_waitcnt lgkmcnt(0)
	v_lshlrev_b32_e32 v253, 2, v218
	s_and_saveexec_b64 s[48:49], s[12:13]
	s_cbranch_execz .LBB0_1364
	global_store_dwordx4 v253, v[156:159], s[46:47]
	global_store_dwordx4 v253, v[144:147], s[46:47] offset:1024
	global_store_dwordx4 v253, v[60:63], s[46:47] offset:16
	global_store_dwordx4 v253, v[48:51], s[46:47] offset:1040
	global_store_dwordx4 v253, v[152:155], s[46:47] offset:512
	global_store_dwordx4 v253, v[132:135], s[46:47] offset:1536
	global_store_dwordx4 v253, v[56:59], s[46:47] offset:528
	global_store_dwordx4 v253, v[36:39], s[46:47] offset:1552

; #define PG8_STAGE(bufoff, gbase, voff) do { _Pragma("unroll") for (int _i = 0; _i < 2; ++_i) \
;         __builtin_amdgcn_global_load_lds((const unsigned*)((const char*)(gbase) + (voff)[_i]), (LAS unsigned*)(lds + (bufoff) + ldsw + _i * 8192), 16, 0, 0); } while (0)
; #define PG8_LDA(dst, b, h) do { _Pragma("unroll") for (int m = 0; m < 4; ++m) _Pragma("unroll") for (int k = 0; k < 2; ++k) dst[m][k] = *(const LAS bf16x8*)(lds + PG8_SA(b, h) + aoff + m * 2048 + k * 1024); } while (0)
; #define PG8_LDB(dst, b, h) do { _Pragma("unroll") for (int n = 0; n < 2; ++n) _Pragma("unroll") for (int k = 0; k < 2; ++k) dst[n][k] = *(const LAS bf16x8*)(lds + PG8_SB(b, h) + boff + n * 2048 + k * 1024); } while (0)
; #define PG8_MMA(ai, bj, At, Bt) do { __builtin_amdgcn_s_setprio(1); _Pragma("unroll") for (int m = 0; m < 4; ++m) _Pragma("unroll") for (int n = 0; n < 2; ++n) _Pragma("unroll") for (int k = 0; k < 2; ++k) \
;         acc[ai][bj][m][n] = __builtin_amdgcn_mfma_f32_16x16x32_bf16(Bt[n][k], At[m][k], acc[ai][bj][m][n], 0, 0, 0); __builtin_amdgcn_s_setprio(0); } while (0)
; #define PG8_WAIT_L(n) asm volatile("s_waitcnt lgkmcnt(" #n ")" ::: "memory")
; #define PG8_BAR __builtin_amdgcn_s_barrier()
; #define PG8_SCHED __builtin_amdgcn_sched_barrier(0)
; template <class Epi>
; __device__ __forceinline__ void gemm_phase(LAS unsigned char* lds, const Gemm g, const StaticOrder& S, const Epi& E) {
;     ...
;             PG8_LDB(B0, 0, 0); PG8_SCHED; PG8_LDA(At, 0, 0); PG8_STAGE(PG8_SA(1, 1), a1 + hstepA, voffA);
;             PG8_WAIT_L(8); PG8_BAR; PG8_WAIT_L(0); PG8_MMA(0, 0, At, B0); PG8_BAR; PG8_SCHED;
;             PG8_LDB(B1, 0, 1); PG8_STAGE(PG8_SB(0, 0), b2, voffB);
;             PG8_BAR; PG8_WAIT_L(0); PG8_MMA(0, 1, At, B1); PG8_BAR;
;             PG8_LDA(At, 0, 1); PG8_STAGE(PG8_SA(0, 0), a2, voffA);
;             PG8_BAR; PG8_WAIT_L(0); PG8_MMA(1, 0, At, B0); PG8_BAR; PG8_SCHED;
.LBB0_1940:
	ds_read_b128 v[96:99], v242
	ds_read_b128 v[100:103], v242 offset:1024
	ds_read_b128 v[104:107], v242 offset:2048
	ds_read_b128 v[108:111], v242 offset:3072
	s_add_u32 s38, s36, 0x100
	s_addc_u32 s39, s37, 0
	s_cmp_eq_u32 s72, 12
	s_cselect_b32 s43, s27, s39
	s_cselect_b32 s42, s68, s38
	s_cselect_b32 s41, s25, s71
	s_cselect_b32 s40, s69, s70
	v_lshl_add_u64 v[176:177], s[36:37], 0, v[224:225]
	s_add_i32 m0, s45, 0xc000
	ds_read_b128 v[112:115], v243
	ds_read_b128 v[116:119], v243 offset:1024
	ds_read_b128 v[120:123], v243 offset:2048
	ds_read_b128 v[124:127], v243 offset:3072
	ds_read_b128 v[160:163], v243 offset:4096
	ds_read_b128 v[164:167], v243 offset:5120
	ds_read_b128 v[168:171], v243 offset:6144
	ds_read_b128 v[172:175], v243 offset:7168
	global_load_lds_dwordx4 v[176:177], off
	v_lshl_add_u64 v[176:177], s[36:37], 0, v[226:227]
	s_add_i32 m0, s45, 0xe000
	s_nop 0
	global_load_lds_dwordx4 v[176:177], off
	ds_read_b128 v[176:179], v244
	ds_read_b128 v[180:183], v244 offset:1024
	ds_read_b128 v[184:187], v244 offset:2048
	ds_read_b128 v[188:191], v244 offset:3072
	s_waitcnt lgkmcnt(0)
	s_barrier
	s_setprio 1
	v_mfma_f32_16x16x32_bf16 v[156:159], v[96:99], v[112:115], v[156:159]
	v_mfma_f32_16x16x32_bf16 v[60:63], v[104:107], v[112:115], v[60:63]
	v_mfma_f32_16x16x32_bf16 v[144:147], v[96:99], v[120:123], v[144:147]
	v_mfma_f32_16x16x32_bf16 v[48:51], v[104:107], v[120:123], v[48:51]
	v_mfma_f32_16x16x32_bf16 v[136:139], v[96:99], v[160:163], v[136:139]
	v_mfma_f32_16x16x32_bf16 v[40:43], v[104:107], v[160:163], v[40:43]
	v_mfma_f32_16x16x32_bf16 v[148:151], v[96:99], v[168:171], v[148:151]
	v_mfma_f32_16x16x32_bf16 v[52:55], v[104:107], v[168:171], v[52:55]
	v_mfma_f32_16x16x32_bf16 v[156:159], v[100:103], v[116:119], v[156:159]
	v_mfma_f32_16x16x32_bf16 v[60:63], v[108:111], v[116:119], v[60:63]
	v_mfma_f32_16x16x32_bf16 v[144:147], v[100:103], v[124:127], v[144:147]
	v_mfma_f32_16x16x32_bf16 v[48:51], v[108:111], v[124:127], v[48:51]
	v_mfma_f32_16x16x32_bf16 v[136:139], v[100:103], v[164:167], v[136:139]
	v_mfma_f32_16x16x32_bf16 v[40:43], v[108:111], v[164:167], v[40:43]
	v_mfma_f32_16x16x32_bf16 v[148:151], v[100:103], v[172:175], v[148:151]
	v_mfma_f32_16x16x32_bf16 v[52:55], v[108:111], v[172:175], v[52:55]
	v_mfma_f32_16x16x32_bf16 v[152:155], v[176:179], v[112:115], v[152:155]
	v_mfma_f32_16x16x32_bf16 v[56:59], v[184:187], v[112:115], v[56:59]
	v_mfma_f32_16x16x32_bf16 v[36:39], v[184:187], v[120:123], v[36:39]
	v_mfma_f32_16x16x32_bf16 v[32:35], v[184:187], v[160:163], v[32:35]
	v_mfma_f32_16x16x32_bf16 v[44:47], v[184:187], v[168:171], v[44:47]
	v_mfma_f32_16x16x32_bf16 v[152:155], v[180:183], v[116:119], v[152:155]
	v_mfma_f32_16x16x32_bf16 v[56:59], v[188:191], v[116:119], v[56:59]
	v_mfma_f32_16x16x32_bf16 v[112:115], v[176:179], v[120:123], v[132:135]
	v_mfma_f32_16x16x32_bf16 v[36:39], v[188:191], v[124:127], v[36:39]
	v_mfma_f32_16x16x32_bf16 v[116:119], v[176:179], v[160:163], v[128:131]
	v_mfma_f32_16x16x32_bf16 v[32:35], v[188:191], v[164:167], v[32:35]
	v_mfma_f32_16x16x32_bf16 v[120:123], v[176:179], v[168:171], v[140:143]
	v_mfma_f32_16x16x32_bf16 v[44:47], v[188:191], v[172:175], v[44:47]
	v_mfma_f32_16x16x32_bf16 v[112:115], v[180:183], v[124:127], v[112:115]
	v_mfma_f32_16x16x32_bf16 v[116:119], v[180:183], v[164:167], v[116:119]
	v_mfma_f32_16x16x32_bf16 v[120:123], v[180:183], v[172:175], v[120:123]
	s_setprio 0
	s_barrier
	s_nop 1
	ds_read_b128 v[124:127], v243 offset:16384
	ds_read_b128 v[128:131], v243 offset:17408
	ds_read_b128 v[132:135], v243 offset:18432
	ds_read_b128 v[140:143], v243 offset:19456
	ds_read_b128 v[160:163], v243 offset:20480
	ds_read_b128 v[164:167], v243 offset:21504
	ds_read_b128 v[168:171], v243 offset:22528
	ds_read_b128 v[172:175], v243 offset:23552
	s_add_i32 s36, s59, s7
	v_lshl_add_u64 v[196:197], s[40:41], 0, v[214:215]
	s_mov_b32 m0, s36
	s_nop 0
	global_load_lds_dwordx4 v[196:197], off
	v_lshl_add_u64 v[198:199], s[40:41], 0, v[210:211]
	s_add_i32 m0, s36, 0x2000
	s_nop 0
	global_load_lds_dwordx4 v[198:199], off
	s_mov_b32 m0, s45
	v_lshl_add_u64 v[200:201], s[42:43], 0, v[216:217]
	global_load_lds_dwordx4 v[200:201], off
	v_lshl_add_u64 v[202:203], s[42:43], 0, v[212:213]
	s_mov_b32 m0, s46
	s_nop 0
	global_load_lds_dwordx4 v[202:203], off
	s_add_u32 s36, s40, 0x40000
	s_addc_u32 s37, s41, 0
	s_add_i32 s73, s62, s7
	v_lshl_add_u64 v[254:255], s[36:37], 0, v[214:215]
	s_mov_b32 m0, s73
	s_nop 0
	global_load_lds_dwordx4 v[254:255], off
	v_lshl_add_u64 v[254:255], s[36:37], 0, v[210:211]
	s_add_i32 m0, s73, 0x2000
	s_nop 0
	global_load_lds_dwordx4 v[254:255], off
	s_waitcnt vmcnt(6)
	s_waitcnt lgkmcnt(0)
	s_barrier
; #define PG8_STAGE(bufoff, gbase, voff) do { _Pragma("unroll") for (int _i = 0; _i < 2; ++_i) \
;         __builtin_amdgcn_global_load_lds((const unsigned*)((const char*)(gbase) + (voff)[_i]), (LAS unsigned*)(lds + (bufoff) + ldsw + _i * 8192), 16, 0, 0); } while (0)
; #define PG8_LDA(dst, b, h) do { _Pragma("unroll") for (int m = 0; m < 4; ++m) _Pragma("unroll") for (int k = 0; k < 2; ++k) dst[m][k] = *(const LAS bf16x8*)(lds + PG8_SA(b, h) + aoff + m * 2048 + k * 1024); } while (0)
; #define PG8_LDB(dst, b, h) do { _Pragma("unroll") for (int n = 0; n < 2; ++n) _Pragma("unroll") for (int k = 0; k < 2; ++k) dst[n][k] = *(const LAS bf16x8*)(lds + PG8_SB(b, h) + boff + n * 2048 + k * 1024); } while (0)
; #define PG8_MMA(ai, bj, At, Bt) do { __builtin_amdgcn_s_setprio(1); _Pragma("unroll") for (int m = 0; m < 4; ++m) _Pragma("unroll") for (int n = 0; n < 2; ++n) _Pragma("unroll") for (int k = 0; k < 2; ++k) \
;         acc[ai][bj][m][n] = __builtin_amdgcn_mfma_f32_16x16x32_bf16(Bt[n][k], At[m][k], acc[ai][bj][m][n], 0, 0, 0); __builtin_amdgcn_s_setprio(0); } while (0)
; #define PG8_WAIT_V(n) asm volatile("s_waitcnt vmcnt(" #n ")" ::: "memory")
; #define PG8_WAIT_L(n) asm volatile("s_waitcnt lgkmcnt(" #n ")" ::: "memory")
; #define PG8_BAR __builtin_amdgcn_s_barrier()
; #define PG8_SCHED __builtin_amdgcn_sched_barrier(0)
; template <class Epi>
; __device__ __forceinline__ void gemm_phase(LAS unsigned char* lds, const Gemm g, const StaticOrder& S, const Epi& E) {
;     ...
;             PG8_BAR; PG8_WAIT_L(0); PG8_MMA(1, 0, At, B0); PG8_BAR; PG8_SCHED;
;             PG8_STAGE(PG8_SB(0, 1), b2 + hstepB, voffB);
;             PG8_WAIT_V(6); PG8_BAR; PG8_MMA(1, 1, At, B1); PG8_BAR;
;             PG8_LDB(B0, 1, 0); PG8_SCHED; PG8_LDA(At, 1, 0); PG8_STAGE(PG8_SA(0, 1), a2 + hstepA, voffA);
;             PG8_WAIT_L(8); PG8_BAR; PG8_WAIT_L(0); PG8_MMA(0, 0, At, B0); PG8_BAR; PG8_SCHED;
;             PG8_LDB(B1, 1, 1); PG8_STAGE(PG8_SB(1, 0), b3, voffB);
;             PG8_BAR; PG8_WAIT_L(0); PG8_MMA(0, 1, At, B1); PG8_BAR;
	s_setprio 1
	v_mfma_f32_16x16x32_bf16 v[92:95], v[96:99], v[124:127], v[92:95]
	v_mfma_f32_16x16x32_bf16 v[28:31], v[104:107], v[124:127], v[28:31]
	v_mfma_f32_16x16x32_bf16 v[80:83], v[96:99], v[132:135], v[80:83]
	v_mfma_f32_16x16x32_bf16 v[16:19], v[104:107], v[132:135], v[16:19]
	v_mfma_f32_16x16x32_bf16 v[76:79], v[96:99], v[160:163], v[76:79]
	v_mfma_f32_16x16x32_bf16 v[12:15], v[104:107], v[160:163], v[12:15]
	v_mfma_f32_16x16x32_bf16 v[84:87], v[96:99], v[168:171], v[84:87]
	v_mfma_f32_16x16x32_bf16 v[20:23], v[104:107], v[168:171], v[20:23]
	v_mfma_f32_16x16x32_bf16 v[92:95], v[100:103], v[128:131], v[92:95]
	v_mfma_f32_16x16x32_bf16 v[28:31], v[108:111], v[128:131], v[28:31]
	v_mfma_f32_16x16x32_bf16 v[80:83], v[100:103], v[140:143], v[80:83]
	v_mfma_f32_16x16x32_bf16 v[16:19], v[108:111], v[140:143], v[16:19]
	v_mfma_f32_16x16x32_bf16 v[76:79], v[100:103], v[164:167], v[76:79]
	v_mfma_f32_16x16x32_bf16 v[12:15], v[108:111], v[164:167], v[12:15]
	v_mfma_f32_16x16x32_bf16 v[84:87], v[100:103], v[172:175], v[84:87]
	v_mfma_f32_16x16x32_bf16 v[20:23], v[108:111], v[172:175], v[20:23]
	v_mfma_f32_16x16x32_bf16 v[88:91], v[176:179], v[124:127], v[88:91]
	v_mfma_f32_16x16x32_bf16 v[24:27], v[184:187], v[124:127], v[24:27]
	v_mfma_f32_16x16x32_bf16 v[68:71], v[176:179], v[132:135], v[68:71]
	v_mfma_f32_16x16x32_bf16 v[4:7], v[184:187], v[132:135], v[4:7]
	v_mfma_f32_16x16x32_bf16 v[64:67], v[176:179], v[160:163], v[64:67]
	v_mfma_f32_16x16x32_bf16 v[0:3], v[184:187], v[160:163], v[0:3]
	v_mfma_f32_16x16x32_bf16 v[72:75], v[176:179], v[168:171], v[72:75]
	v_mfma_f32_16x16x32_bf16 v[8:11], v[184:187], v[168:171], v[8:11]
	v_mfma_f32_16x16x32_bf16 v[88:91], v[180:183], v[128:131], v[88:91]
	v_mfma_f32_16x16x32_bf16 v[24:27], v[188:191], v[128:131], v[24:27]
	v_mfma_f32_16x16x32_bf16 v[68:71], v[180:183], v[140:143], v[68:71]
	v_mfma_f32_16x16x32_bf16 v[4:7], v[188:191], v[140:143], v[4:7]
	v_mfma_f32_16x16x32_bf16 v[64:67], v[180:183], v[164:167], v[64:67]
	v_mfma_f32_16x16x32_bf16 v[0:3], v[188:191], v[164:167], v[0:3]
	v_mfma_f32_16x16x32_bf16 v[72:75], v[180:183], v[172:175], v[72:75]
	v_mfma_f32_16x16x32_bf16 v[8:11], v[188:191], v[172:175], v[8:11]
	s_setprio 0
	s_add_i32 s73, 0, 0x18000
	v_add_u32_e32 v108, s73, v234
	s_barrier
	ds_read_b128 v[96:99], v108
	ds_read_b128 v[100:103], v108 offset:1024
	ds_read_b128 v[104:107], v108 offset:2048
	ds_read_b128 v[108:111], v108 offset:3072
	s_add_u32 s36, s42, 0x40000
	s_addc_u32 s37, s43, 0
	s_mov_b32 m0, s47
	v_lshl_add_u64 v[132:133], s[36:37], 0, v[216:217]
	ds_read_b128 v[124:127], v243 offset:32768
	ds_read_b128 v[128:131], v243 offset:33792
	ds_read_b128 v[140:143], v243 offset:34816
	ds_read_b128 v[160:163], v243 offset:35840
	ds_read_b128 v[164:167], v243 offset:36864
	ds_read_b128 v[168:171], v243 offset:37888
	ds_read_b128 v[172:175], v243 offset:38912
	ds_read_b128 v[176:179], v243 offset:39936
	global_load_lds_dwordx4 v[132:133], off
	v_lshl_add_u64 v[132:133], s[36:37], 0, v[212:213]
	s_mov_b32 m0, s48
	s_nop 0
	global_load_lds_dwordx4 v[132:133], off
	s_add_i32 s42, 0, 0x1c000
	v_add_u32_e32 v132, s42, v234
	ds_read_b128 v[180:183], v132
	ds_read_b128 v[184:187], v132 offset:1024
	ds_read_b128 v[188:191], v132 offset:2048
	ds_read_b128 v[192:195], v132 offset:3072
	s_waitcnt lgkmcnt(0)
	s_barrier
	s_setprio 1
	v_mfma_f32_16x16x32_bf16 v[132:135], v[96:99], v[124:127], v[156:159]
	v_mfma_f32_16x16x32_bf16 v[156:159], v[100:103], v[128:131], v[132:135]
	v_mfma_f32_16x16x32_bf16 v[132:135], v[96:99], v[140:143], v[144:147]
	v_mfma_f32_16x16x32_bf16 v[144:147], v[100:103], v[160:163], v[132:135]
	v_mfma_f32_16x16x32_bf16 v[132:135], v[96:99], v[164:167], v[136:139]
	v_mfma_f32_16x16x32_bf16 v[60:63], v[104:107], v[124:127], v[60:63]
	v_mfma_f32_16x16x32_bf16 v[48:51], v[104:107], v[140:143], v[48:51]
	v_mfma_f32_16x16x32_bf16 v[136:139], v[100:103], v[168:171], v[132:135]
	v_mfma_f32_16x16x32_bf16 v[40:43], v[104:107], v[164:167], v[40:43]
	v_mfma_f32_16x16x32_bf16 v[132:135], v[96:99], v[172:175], v[148:151]
	v_mfma_f32_16x16x32_bf16 v[52:55], v[104:107], v[172:175], v[52:55]
	v_mfma_f32_16x16x32_bf16 v[60:63], v[108:111], v[128:131], v[60:63]
	v_mfma_f32_16x16x32_bf16 v[48:51], v[108:111], v[160:163], v[48:51]
	v_mfma_f32_16x16x32_bf16 v[40:43], v[108:111], v[168:171], v[40:43]
	v_mfma_f32_16x16x32_bf16 v[148:151], v[100:103], v[176:179], v[132:135]
	v_mfma_f32_16x16x32_bf16 v[52:55], v[108:111], v[176:179], v[52:55]
	v_mfma_f32_16x16x32_bf16 v[132:135], v[180:183], v[124:127], v[152:155]
	v_mfma_f32_16x16x32_bf16 v[112:115], v[180:183], v[140:143], v[112:115]
	v_mfma_f32_16x16x32_bf16 v[152:155], v[184:187], v[128:131], v[132:135]
	v_mfma_f32_16x16x32_bf16 v[56:59], v[188:191], v[124:127], v[56:59]
	v_mfma_f32_16x16x32_bf16 v[132:135], v[184:187], v[160:163], v[112:115]
	v_mfma_f32_16x16x32_bf16 v[112:115], v[180:183], v[164:167], v[116:119]
	v_mfma_f32_16x16x32_bf16 v[56:59], v[192:195], v[128:131], v[56:59]
	v_mfma_f32_16x16x32_bf16 v[36:39], v[188:191], v[140:143], v[36:39]
	v_mfma_f32_16x16x32_bf16 v[128:131], v[184:187], v[168:171], v[112:115]
	v_mfma_f32_16x16x32_bf16 v[32:35], v[188:191], v[164:167], v[32:35]
	v_mfma_f32_16x16x32_bf16 v[112:115], v[180:183], v[172:175], v[120:123]
	v_mfma_f32_16x16x32_bf16 v[44:47], v[188:191], v[172:175], v[44:47]
	v_mfma_f32_16x16x32_bf16 v[36:39], v[192:195], v[160:163], v[36:39]
	v_mfma_f32_16x16x32_bf16 v[32:35], v[192:195], v[168:171], v[32:35]
	v_mfma_f32_16x16x32_bf16 v[140:143], v[184:187], v[176:179], v[112:115]
	v_mfma_f32_16x16x32_bf16 v[44:47], v[192:195], v[176:179], v[44:47]
	s_setprio 0
	s_barrier
; #define PG8_STAGE(bufoff, gbase, voff) do { _Pragma("unroll") for (int _i = 0; _i < 2; ++_i) \
;         __builtin_amdgcn_global_load_lds((const unsigned*)((const char*)(gbase) + (voff)[_i]), (LAS unsigned*)(lds + (bufoff) + ldsw + _i * 8192), 16, 0, 0); } while (0)
; #define PG8_LDA(dst, b, h) do { _Pragma("unroll") for (int m = 0; m < 4; ++m) _Pragma("unroll") for (int k = 0; k < 2; ++k) dst[m][k] = *(const LAS bf16x8*)(lds + PG8_SA(b, h) + aoff + m * 2048 + k * 1024); } while (0)
; #define PG8_MMA(ai, bj, At, Bt) do { __builtin_amdgcn_s_setprio(1); _Pragma("unroll") for (int m = 0; m < 4; ++m) _Pragma("unroll") for (int n = 0; n < 2; ++n) _Pragma("unroll") for (int k = 0; k < 2; ++k) \
;         acc[ai][bj][m][n] = __builtin_amdgcn_mfma_f32_16x16x32_bf16(Bt[n][k], At[m][k], acc[ai][bj][m][n], 0, 0, 0); __builtin_amdgcn_s_setprio(0); } while (0)
; #define PG8_WAIT_V(n) asm volatile("s_waitcnt vmcnt(" #n ")" ::: "memory")
; #define PG8_WAIT_L(n) asm volatile("s_waitcnt lgkmcnt(" #n ")" ::: "memory")
; #define PG8_BAR __builtin_amdgcn_s_barrier()
; #define PG8_SCHED __builtin_amdgcn_sched_barrier(0)
; template <class Epi>
; __device__ __forceinline__ void gemm_phase(LAS unsigned char* lds, const Gemm g, const StaticOrder& S, const Epi& E) {
;     ...
;             PG8_LDA(At, 1, 1); PG8_STAGE(PG8_SA(1, 0), a3, voffA);
;             PG8_BAR; PG8_WAIT_L(0); PG8_MMA(1, 0, At, B0); PG8_BAR; PG8_SCHED;
;             PG8_STAGE(PG8_SB(1, 1), b3 + hstepB, voffB);
;             PG8_WAIT_V(6); PG8_BAR; PG8_MMA(1, 1, At, B1); PG8_BAR;
;     __device__ __forceinline__ void operator()(AccRef acc, const Unit& u, int wr, int wc, int fr, int fq) const {
;     ...
;         { const float* cv = cw + 128 * u.pn + clb; const float* cg = cv + FH; const float* bp = cb + 128 * u.pn + clb;
;           cwv[0][0] = *(const f32x4*)(cv); cwv[0][1] = *(const f32x4*)(cv + F2); cwv[0][2] = *(const f32x4*)(cv + 2 * F2); cwv[0][3] = *(const f32x4*)(bp);
;           cwv[0][4] = *(const f32x4*)(cg); cwv[0][5] = *(const f32x4*)(cg + F2); cwv[0][6] = *(const f32x4*)(cg + 2 * F2); cwv[0][7] = *(const f32x4*)(bp + FH); }
	s_nop 1
	ds_read_b128 v[112:115], v243 offset:49152
	ds_read_b128 v[116:119], v243 offset:50176
	ds_read_b128 v[120:123], v243 offset:51200
	ds_read_b128 v[124:127], v243 offset:52224
	ds_read_b128 v[160:163], v243 offset:53248
	ds_read_b128 v[164:167], v243 offset:54272
	ds_read_b128 v[168:171], v243 offset:55296
	ds_read_b128 v[172:175], v243 offset:56320
	s_add_i32 s36, s73, s7
	v_lshl_add_u64 v[254:255], v[196:197], 0, s[16:17]
	s_mov_b32 m0, s36
	s_nop 0
	global_load_lds_dwordx4 v[254:255], off
	v_lshl_add_u64 v[254:255], v[198:199], 0, s[16:17]
	s_add_i32 m0, s36, 0x2000
	s_nop 0
	global_load_lds_dwordx4 v[254:255], off
	s_mov_b32 m0, s57
	v_lshl_add_u64 v[254:255], v[200:201], 0, s[16:17]
	global_load_lds_dwordx4 v[254:255], off
	v_lshl_add_u64 v[254:255], v[202:203], 0, s[16:17]
	s_mov_b32 m0, s58
	s_nop 0
	global_load_lds_dwordx4 v[254:255], off
	s_add_u32 s36, s40, 0x40080
	s_addc_u32 s37, s41, 0
	s_add_i32 s40, s42, s7
	v_lshl_add_u64 v[254:255], s[36:37], 0, v[214:215]
	s_mov_b32 m0, s40
	s_nop 0
	global_load_lds_dwordx4 v[254:255], off
	v_lshl_add_u64 v[254:255], s[36:37], 0, v[210:211]
	s_add_i32 m0, s40, 0x2000
	s_nop 0
	global_load_lds_dwordx4 v[254:255], off
	s_waitcnt vmcnt(6)
	s_waitcnt lgkmcnt(0)
	s_barrier
	s_setprio 1
	v_mfma_f32_16x16x32_bf16 v[92:95], v[96:99], v[112:115], v[92:95]
	v_mfma_f32_16x16x32_bf16 v[28:31], v[104:107], v[112:115], v[28:31]
	v_mfma_f32_16x16x32_bf16 v[80:83], v[96:99], v[120:123], v[80:83]
	v_mfma_f32_16x16x32_bf16 v[16:19], v[104:107], v[120:123], v[16:19]
	v_mfma_f32_16x16x32_bf16 v[76:79], v[96:99], v[160:163], v[76:79]
	v_mfma_f32_16x16x32_bf16 v[12:15], v[104:107], v[160:163], v[12:15]
	v_mfma_f32_16x16x32_bf16 v[84:87], v[96:99], v[168:171], v[84:87]
	v_mfma_f32_16x16x32_bf16 v[20:23], v[104:107], v[168:171], v[20:23]
	v_mfma_f32_16x16x32_bf16 v[92:95], v[100:103], v[116:119], v[92:95]
	v_mfma_f32_16x16x32_bf16 v[28:31], v[108:111], v[116:119], v[28:31]
	v_mfma_f32_16x16x32_bf16 v[80:83], v[100:103], v[124:127], v[80:83]
	v_mfma_f32_16x16x32_bf16 v[16:19], v[108:111], v[124:127], v[16:19]
	v_mfma_f32_16x16x32_bf16 v[76:79], v[100:103], v[164:167], v[76:79]
	v_mfma_f32_16x16x32_bf16 v[12:15], v[108:111], v[164:167], v[12:15]
	v_mfma_f32_16x16x32_bf16 v[84:87], v[100:103], v[172:175], v[84:87]
	v_mfma_f32_16x16x32_bf16 v[20:23], v[108:111], v[172:175], v[20:23]
	v_mfma_f32_16x16x32_bf16 v[88:91], v[180:183], v[112:115], v[88:91]
	v_mfma_f32_16x16x32_bf16 v[24:27], v[188:191], v[112:115], v[24:27]
	v_mfma_f32_16x16x32_bf16 v[68:71], v[180:183], v[120:123], v[68:71]
	v_mfma_f32_16x16x32_bf16 v[4:7], v[188:191], v[120:123], v[4:7]
	v_mfma_f32_16x16x32_bf16 v[64:67], v[180:183], v[160:163], v[64:67]
	v_mfma_f32_16x16x32_bf16 v[0:3], v[188:191], v[160:163], v[0:3]
	v_mfma_f32_16x16x32_bf16 v[72:75], v[180:183], v[168:171], v[72:75]
	v_mfma_f32_16x16x32_bf16 v[8:11], v[188:191], v[168:171], v[8:11]
	v_mfma_f32_16x16x32_bf16 v[88:91], v[184:187], v[116:119], v[88:91]
	v_mfma_f32_16x16x32_bf16 v[24:27], v[192:195], v[116:119], v[24:27]
	v_mfma_f32_16x16x32_bf16 v[68:71], v[184:187], v[124:127], v[68:71]
	v_mfma_f32_16x16x32_bf16 v[4:7], v[192:195], v[124:127], v[4:7]
	v_mfma_f32_16x16x32_bf16 v[64:67], v[184:187], v[164:167], v[64:67]
	v_mfma_f32_16x16x32_bf16 v[0:3], v[192:195], v[164:167], v[0:3]
	v_mfma_f32_16x16x32_bf16 v[72:75], v[184:187], v[172:175], v[72:75]
	v_mfma_f32_16x16x32_bf16 v[8:11], v[192:195], v[172:175], v[8:11]
	s_setprio 0
	s_add_i32 s72, s72, 2
	s_add_u32 s70, s70, 0x100
	s_addc_u32 s71, s71, 0
	s_cmp_gt_u32 s72, 13
	s_mov_b64 s[36:37], s[38:39]
	s_barrier
	s_cbranch_scc0 .LBB0_1940
	s_lshl_b32 s36, s35, 7
	s_ashr_i32 s37, s36, 31
	s_lshl_b64 s[38:39], s[36:37], 2
	v_readfirstlane_b32 s99, v219
	v_and_b32_e32 v96, 15, v219
	v_and_b32_e32 v97, 3, v96
	v_mul_u32_u24_e32 v98, 0x5800, v97
	v_cmp_eq_u32_e32 vcc, 3, v97
	v_bfe_u32 v99, v96, 2, 1
	v_mul_u32_u24_e32 v99, 0x2c00, v99
	v_cndmask_b32_e64 v98, v98, 0, vcc
	v_add_u32_e32 v98, v98, v99
	v_bfe_u32 v99, v96, 3, 1
	v_lshl_add_u32 v98, v99, 4, v98
	v_add_u32_e32 v98, s38, v98
	v_cndmask_b32_e32 v100, v220, v222, vcc
	v_cndmask_b32_e32 v101, v221, v223, vcc
	v_add_co_u32_e32 v100, vcc, v100, v98
	s_nop 1
	v_addc_co_u32_e32 v101, vcc, 0, v101, vcc
	s_bitcmp1_b32 s99, 8
	s_cbranch_scc1 .Lcw1940_skip
	global_load_dwordx4 v[108:111], v[100:101], off
;     __device__ __forceinline__ void operator()(AccRef acc, const Unit& u, int wr, int wc, int fr, int fq) const {
;         const int clb = 32 * wc + 8 * fq;
;         f32x4 cwv[2][8];
;         { const float* cv = cw + 128 * u.pn + clb; const float* cg = cv + FH; const float* bp = cb + 128 * u.pn + clb;
;           cwv[0][0] = *(const f32x4*)(cv); cwv[0][1] = *(const f32x4*)(cv + F2); cwv[0][2] = *(const f32x4*)(cv + 2 * F2); cwv[0][3] = *(const f32x4*)(bp);
;           cwv[0][4] = *(const f32x4*)(cg); cwv[0][5] = *(const f32x4*)(cg + F2); cwv[0][6] = *(const f32x4*)(cg + 2 * F2); cwv[0][7] = *(const f32x4*)(bp + FH); }
;         if (fr == 15) {
; #pragma unroll
;             for (int ai = 0; ai < 2; ++ai)
; #pragma unroll
;                 for (int bj = 0; bj < 2; ++bj)
; #pragma unroll
;                     for (int n = 0; n < 2; ++n) { *(LAS f32x4*)(xch + ((ai * 2 + wr) * 2 + 0) * 256 + bj * 128 + clb + 4 * n) = acc[ai][bj][2][n]; *(LAS f32x4*)(xch + ((ai * 2 + wr) * 2 + 1) * 256 + bj * 128 + clb + 4 * n) = acc[ai][bj][3][n]; }
;         }
;         float* rawu = raw + (size_t)(u.pm * 22 + u.pn) * 1024;
;         if (wr == 0 && fr == 0) {
; #pragma unroll
;             for (int bj = 0; bj < 2; ++bj)
; #pragma unroll
;                 for (int n = 0; n < 2; ++n) { *(f32x4*)(rawu + 0 * 256 + bj * 128 + clb + 4 * n) = acc[0][bj][0][n]; *(f32x4*)(rawu + 1 * 256 + bj * 128 + clb + 4 * n) = acc[0][bj][1][n]; }
;         }
;         if (wr == 1 && fr == 15) {
; #pragma unroll
;             for (int bj = 0; bj < 2; ++bj)
; #pragma unroll
;                 for (int n = 0; n < 2; ++n) { *(f32x4*)(rawu + 2 * 256 + bj * 128 + clb + 4 * n) = acc[1][bj][2][n]; *(f32x4*)(rawu + 3 * 256 + bj * 128 + clb + 4 * n) = acc[1][bj][3][n]; }
;         }
;         asm volatile("s_waitcnt lgkmcnt(0)" ::: "memory"); __builtin_amdgcn_s_barrier(); __builtin_amdgcn_s_barrier(); asm volatile("" ::: "memory");
;         const int hc0 = 128 * u.pn + clb, row0 = u.pm * 256 + wr * 64 + 4 * fr;
; #pragma unroll
;         for (int n = 0; n < 2; ++n) {
;             const f32x4 w0v = cwv[n][0], w1v = cwv[n][1], w2v = cwv[n][2], bvv = cwv[n][3], w0g = cwv[n][4], w1g = cwv[n][5], w2g = cwv[n][6], bvg = cwv[n][7];
; #pragma unroll
;             for (int ai = 0; ai < 2; ++ai) {
;                 if (n == 0 && ai == 0) {
;                     asm volatile("" ::: "memory");
.Lcw1940_skip:
	s_and_saveexec_b64 s[38:39], s[0:1]
	s_cbranch_execz .LBB0_1943
	ds_write_b128 v236, v[136:139]
	ds_write_b128 v236, v[148:151] offset:1024
	ds_write_b128 v236, v[40:43] offset:16
	ds_write_b128 v236, v[52:55] offset:1040
	ds_write_b128 v236, v[128:131] offset:512
	ds_write_b128 v236, v[140:143] offset:1536
	ds_write_b128 v236, v[32:35] offset:528
	ds_write_b128 v236, v[44:47] offset:1552
	ds_write_b128 v236, v[76:79] offset:4096
	ds_write_b128 v236, v[84:87] offset:5120
	ds_write_b128 v236, v[12:15] offset:4112
	ds_write_b128 v236, v[20:23] offset:5136
	ds_write_b128 v236, v[64:67] offset:4608
	ds_write_b128 v236, v[72:75] offset:5632
	ds_write_b128 v236, v[0:3] offset:4624
	ds_write_b128 v236, v[8:11] offset:5648
.LBB0_1943:
	s_or_b64 exec, exec, s[38:39]
	s_mul_i32 s25, s34, 22
	s_add_i32 s38, s25, s35
	s_ashr_i32 s39, s38, 31
	s_lshl_b64 s[38:39], s[38:39], 12
	s_add_u32 s38, s64, s38
	s_addc_u32 s39, s65, s39
	v_lshlrev_b32_e32 v96, 2, v218
	v_or_b32_e32 v232, s36, v218
	v_ashrrev_i32_e32 v233, 31, v232
	v_lshlrev_b64 v[96:97], 2, v[232:233]
	v_lshl_add_u64 v[120:121], s[12:13], 0, v[96:97]
	v_add_co_u32_e32 v100, vcc, 0x5000, v120
	s_bitcmp1_b32 s99, 8
	s_cbranch_scc1 .Lcw1940_nostage
	s_waitcnt vmcnt(0)
	v_and_b32_e32 v107, 0xff, v219
	v_lshlrev_b32_e32 v107, 4, v107
	v_add_u32_e32 v107, 0x22000, v107
	ds_write_b128 v107, v[108:111]
.Lcw1940_nostage:
	s_waitcnt lgkmcnt(0)
	s_barrier
	s_nop 0
	v_addc_co_u32_e32 v101, vcc, 0, v121, vcc
	v_add_co_u32_e32 v104, vcc, 0xb000, v120
	s_barrier
	s_nop 0
	v_addc_co_u32_e32 v105, vcc, 0, v121, vcc
	v_add_co_u32_e32 v112, vcc, s49, v120
	v_lshl_add_u64 v[124:125], s[14:15], 0, v[96:97]
	s_nop 0
	v_addc_co_u32_e32 v113, vcc, 0, v121, vcc
	v_add_co_u32_e32 v116, vcc, 0x8000, v120
	s_nop 0
	s_nop 0
	v_addc_co_u32_e32 v117, vcc, 0, v121, vcc
	v_add_co_u32_e32 v120, vcc, 0xd000, v120
	s_nop 0
	s_nop 0
	v_addc_co_u32_e32 v121, vcc, 0, v121, vcc
	v_add_co_u32_e32 v124, vcc, 0x2000, v124
	s_nop 0
	s_nop 0
	v_addc_co_u32_e32 v125, vcc, 0, v125, vcc
	v_mov_b32_e32 v192, 0
	v_mov_b32_e32 v198, 0
	v_mov_b32_e32 v199, 0
	v_mov_b32_e32 v200, 0
	v_mov_b32_e32 v201, 0
	v_mov_b32_e32 v206, 0
	v_mov_b32_e32 v207, 0
	v_mov_b32_e32 v208, 0
	v_mov_b32_e32 v209, 0
	v_mov_b32_e32 v194, 0
	v_mov_b32_e32 v195, 0
	v_mov_b32_e32 v196, 0
	v_mov_b32_e32 v197, 0
	v_mov_b32_e32 v202, 0
	v_mov_b32_e32 v203, 0
	v_mov_b32_e32 v204, 0
	v_mov_b32_e32 v205, 0
	s_and_saveexec_b64 s[36:37], s[20:21]
	s_cbranch_execz .LBB0_1949
	ds_read_b128 v[202:205], v237
	ds_read_b128 v[206:209], v237 offset:512
	ds_read_b128 v[194:197], v237 offset:1024
	ds_read_b128 v[198:201], v237 offset:1536
.LBB0_1949:
	s_or_b64 exec, exec, s[36:37]
	s_waitcnt lgkmcnt(0)
	v_mov_b32_dpp v198, v140 row_shr:1 row_mask:0xf bank_mask:0xf
	v_mov_b32_dpp v199, v141 row_shr:1 row_mask:0xf bank_mask:0xf
	s_waitcnt vmcnt(8)
	v_and_b32_e32 v253, 0xf0, v219
	v_lshlrev_b32_e32 v253, 4, v253
	v_add_u32_e32 v253, 0x22000, v253
	ds_read_b128 v[160:163], v253
	ds_read_b128 v[164:167], v253 offset:16
	ds_read_b128 v[168:171], v253 offset:32
	ds_read_b128 v[172:175], v253 offset:48
	ds_read_b128 v[176:179], v253 offset:64
	ds_read_b128 v[180:183], v253 offset:80
	ds_read_b128 v[184:187], v253 offset:96
	ds_read_b128 v[188:191], v253 offset:112
	ds_read_b128 v[96:99], v253 offset:128
	ds_read_b128 v[100:103], v253 offset:144
	ds_read_b128 v[104:107], v253 offset:160
	ds_read_b128 v[108:111], v253 offset:176
	ds_read_b128 v[112:115], v253 offset:192
	ds_read_b128 v[116:119], v253 offset:208
	ds_read_b128 v[120:123], v253 offset:224
	ds_read_b128 v[124:127], v253 offset:240
	s_waitcnt lgkmcnt(0)
	v_lshlrev_b32_e32 v253, 2, v218
	s_and_saveexec_b64 s[40:41], s[8:9]
	s_cbranch_execz .LBB0_1945
	global_store_dwordx4 v253, v[156:159], s[38:39]
	global_store_dwordx4 v253, v[144:147], s[38:39] offset:1024
	global_store_dwordx4 v253, v[60:63], s[38:39] offset:16
	global_store_dwordx4 v253, v[48:51], s[38:39] offset:1040
	global_store_dwordx4 v253, v[152:155], s[38:39] offset:512
	global_store_dwordx4 v253, v[132:135], s[38:39] offset:1536
	global_store_dwordx4 v253, v[56:59], s[38:39] offset:528
	global_store_dwordx4 v253, v[36:39], s[38:39] offset:1552
